# P3 weight copies rewritten as a software-pipelined loop (loads of 2 items ahead in flight, fully unrolled 20 items per wave)
# speedup vs baseline: 1.0159x; 1.0010x over previous
; #define GAS __attribute__((address_space(1)))
; #define LAS __attribute__((address_space(3)))
; #define LDS_WAIT() asm volatile("s_waitcnt lgkmcnt(0)" ::: "memory")
; __device__ __forceinline__ void p0_transpose_item(const float* W, int ldw, int src_col0, int k0, bf16_t* WT, int ldk, int dst_row0, int dst_k0, LAS float* scr, int lane) {
; #pragma unroll
;     for (int i = 0; i < 8; ++i) { const int kk = 8 * i + (lane >> 3), n4 = 4 * (lane & 7);
;         const f32x4 w = *(const GAS f32x4*)(W + (size_t)(k0 + kk) * ldw + src_col0 + n4); LAS float* d = scr + kk * 33 + n4; d[0] = w[0]; d[1] = w[1]; d[2] = w[2]; d[3] = w[3]; }
;     LDS_WAIT(); asm volatile("" ::: "memory");
;     const int c = lane & 7;
; #pragma unroll
;     for (int j = 0; j < 4; ++j) { const int n = (lane >> 3) + 8 * j; const LAS float* s = scr + (8 * c) * 33 + n;
;         v4u o; o.x = pk2(s[0 * 33], s[1 * 33]); o.y = pk2(s[2 * 33], s[3 * 33]); o.z = pk2(s[4 * 33], s[5 * 33]); o.w = pk2(s[6 * 33], s[7 * 33]);
;         *(GAS v4u*)(WT + (size_t)(dst_row0 + n) * ldk + dst_k0 + k0 + 8 * c) = o; }
;     LDS_WAIT(); asm volatile("" ::: "memory");
; __global__ void __launch_bounds__(NWAVES * 64, 2) fwd(Args args) {
;     ...
;                 if (blockIdx.x < 64) for (int it = ((int)blockIdx.x - 32) * NWAVES + wave; it < I_BA + I_BB + I_O + I_UP + I_DN; it += 32 * NWAVES) {
;                     int r = it;
;                     if (r < I_BA) { const int kb = r / 32, nb = r % 32; p0_transpose_item(wba, 1024, 32 * nb, 64 * kb, WBAB_T, 1024, 32 * nb, 0, scr, lane); continue; } r -= I_BA;
;                     if (r < I_BB) { const int kb = r / 32, nb = r % 32; p0_transpose_item(wbb, 1024, 32 * nb, 64 * kb, WBAB_T, 1024, 32 * nb, 512, scr, lane); continue; } r -= I_BB;
;                     if (r < I_O) { const int kb = r / 32, nb = r % 32; p0_transpose_item(wo, 1024, 32 * nb, 64 * kb, WO_T, 1024, 32 * nb, 0, scr, lane); continue; } r -= I_O;
;                     if (r < I_UP) { const int kb = r / 128, nb = r % 128; p0_transpose_item(wup, FF, 32 * nb, 64 * kb, WUP_T, 1024, 32 * nb, 0, scr, lane); continue; } r -= I_UP;
;                     { const int kb = r / 32, nb = r % 32; p0_transpose_item(wdn, 1024, 32 * nb, 64 * kb, WDN_T, FF, 32 * nb, 0, scr, lane); }
.LBB0_818:
	s_andn2_b64 vcc, exec, s[38:39]
	s_waitcnt vmcnt(0)
	s_barrier
	s_cbranch_vccnz .LBB0_839
	s_add_i32 s0, s72, s48
	s_add_i32 s4, s0, 0xffffff00
	s_cmp_lt_i32 s4, 0
	s_cbranch_scc1 .LBB0_839
	s_cmpk_gt_i32 s4, 0xff
	s_cbranch_scc1 .LBB0_839
	v_readlane_b32 s68, v240, 8
	v_readlane_b32 s69, v240, 9
	v_readlane_b32 s70, v240, 10
	v_readlane_b32 s71, v240, 11
	v_readlane_b32 s74, v240, 12
	v_readlane_b32 s75, v240, 13
	v_readlane_b32 s78, v240, 18
	v_readlane_b32 s79, v240, 19
	v_readlane_b32 s80, v240, 20
	v_readlane_b32 s81, v240, 21
	v_and_b32_e32 v2, 7, v234
	v_lshrrev_b32_e32 v1, 3, v234
	v_lshlrev_b32_e32 v3, 4, v2
	s_mul_i32 s0, s48, 0x2200
	v_mul_u32_u24_e32 v4, 0x84, v1
	v_add3_u32 v32, s0, v3, v4
	v_add_u32_e32 v33, 0x420, v32
	v_add_u32_e32 v34, 0x428, v32
	v_add_u32_e32 v35, 0x840, v32
	v_add_u32_e32 v36, 0x848, v32
	v_add_u32_e32 v37, 0xc60, v32
	v_add_u32_e32 v38, 0xc68, v32
	v_add_u32_e32 v39, 0x1080, v32
	v_add_u32_e32 v40, 0x1088, v32
	v_add_u32_e32 v41, 0x14a0, v32
	v_add_u32_e32 v42, 0x14a8, v32
	v_add_u32_e32 v43, 0x18c0, v32
	v_add_u32_e32 v44, 0x18c8, v32
	v_add_u32_e32 v45, 0x1ce0, v32
	v_add_u32_e32 v46, 0x1ce8, v32
	v_lshlrev_b32_e32 v5, 3, v2
	v_mul_u32_u24_e32 v5, 0x84, v5
	v_lshlrev_b32_e32 v6, 2, v1
	v_add3_u32 v31, s0, v5, v6
	v_lshl_or_b32 v100, v1, 12, v3
	v_add_u32_e32 v101, 0x8000, v100
	v_add_u32_e32 v102, 0x10000, v100
	v_add_u32_e32 v103, 0x18000, v100
	v_add_u32_e32 v104, 0x20000, v100
	v_add_u32_e32 v105, 0x28000, v100
	v_add_u32_e32 v106, 0x30000, v100
	v_add_u32_e32 v107, 0x38000, v100
	v_lshl_or_b32 v108, v1, 14, v3
	v_add_u32_e32 v109, 0x20000, v108
	v_add_u32_e32 v110, 0x40000, v108
	v_add_u32_e32 v111, 0x60000, v108
	v_add_u32_e32 v112, 0x80000, v108
	v_add_u32_e32 v113, 0xa0000, v108
	v_add_u32_e32 v114, 0xc0000, v108
	v_add_u32_e32 v115, 0xe0000, v108
	v_lshl_or_b32 v116, v1, 11, v3
	v_add_u32_e32 v117, 0x4000, v116
	v_add_u32_e32 v118, 0x8000, v116
	v_add_u32_e32 v119, 0xc000, v116
	v_lshl_or_b32 v120, v1, 13, v3
	v_add_u32_e32 v121, 0x10000, v120
	v_add_u32_e32 v122, 0x20000, v120
	v_add_u32_e32 v123, 0x30000, v120
	s_lshr_b32 s5, s4, 5
	s_and_b32 s6, s4, 31
	s_lshr_b32 s7, s4, 7
	s_and_b32 s8, s4, 0x7f
	s_lshl_b32 s9, s5, 18
	s_lshl_b32 s10, s6, 7
	s_add_u32 s9, s9, s10
	s_lshl_b32 s10, s7, 20
	s_lshl_b32 s11, s8, 7
	s_add_u32 s10, s10, s11
	s_add_u32 s40, s68, s9
	s_addc_u32 s41, s69, 0
	s_add_u32 s42, s70, s9
	s_addc_u32 s43, s71, 0
	s_add_u32 s44, s74, s9
	s_addc_u32 s45, s75, 0
	s_add_u32 s46, s78, s10
	s_addc_u32 s47, s79, 0
	s_add_u32 s50, s80, s9
	s_addc_u32 s51, s81, 0
	s_lshl_b32 s9, s6, 16
	s_lshl_b32 s11, s5, 7
	s_add_u32 s9, s9, s11
	s_lshl_b32 s10, s8, 16
	s_lshl_b32 s19, s7, 7
	s_add_u32 s10, s10, s19
	s_lshl_b32 s18, s6, 18
	s_add_u32 s18, s18, s11
	s_add_u32 s82, s22, s9
	s_addc_u32 s83, s23, 0
	s_add_u32 s84, s16, s9
	s_addc_u32 s85, s17, 0
	s_add_u32 s86, s14, s10
	s_addc_u32 s87, s15, 0
	s_add_u32 s88, s12, s18
	s_addc_u32 s89, s13, 0
	s_add_u32 s76, s88, 0x1000
	s_addc_u32 s77, s89, 0
	global_load_dwordx4 v[128:131], v100, s[40:41] nt
	global_load_dwordx4 v[132:135], v101, s[40:41] nt
	global_load_dwordx4 v[136:139], v102, s[40:41] nt
	global_load_dwordx4 v[140:143], v103, s[40:41] nt
	global_load_dwordx4 v[144:147], v104, s[40:41] nt
	global_load_dwordx4 v[148:151], v105, s[40:41] nt
	global_load_dwordx4 v[152:155], v106, s[40:41] nt
	global_load_dwordx4 v[156:159], v107, s[40:41] nt
	global_load_dwordx4 v[160:163], v100, s[42:43] nt
	global_load_dwordx4 v[164:167], v101, s[42:43] nt
	global_load_dwordx4 v[168:171], v102, s[42:43] nt
	global_load_dwordx4 v[172:175], v103, s[42:43] nt
	global_load_dwordx4 v[176:179], v104, s[42:43] nt
	global_load_dwordx4 v[180:183], v105, s[42:43] nt
	global_load_dwordx4 v[184:187], v106, s[42:43] nt
	global_load_dwordx4 v[188:191], v107, s[42:43] nt
	global_load_dwordx4 v[192:195], v100, s[44:45] nt
	global_load_dwordx4 v[196:199], v101, s[44:45] nt
	global_load_dwordx4 v[200:203], v102, s[44:45] nt
	global_load_dwordx4 v[204:207], v103, s[44:45] nt
	global_load_dwordx4 v[208:211], v104, s[44:45] nt
	global_load_dwordx4 v[212:215], v105, s[44:45] nt
	global_load_dwordx4 v[216:219], v106, s[44:45] nt
	global_load_dwordx4 v[220:223], v107, s[44:45] nt
	s_waitcnt vmcnt(16)
	ds_write2_b32 v32, v128, v129 offset1:1
	ds_write2_b32 v32, v130, v131 offset0:2 offset1:3
	ds_write2_b32 v33, v132, v133 offset1:1
	ds_write2_b32 v34, v134, v135 offset1:1
	ds_write2_b32 v35, v136, v137 offset1:1
	ds_write2_b32 v36, v138, v139 offset1:1
	ds_write2_b32 v37, v140, v141 offset1:1
	ds_write2_b32 v38, v142, v143 offset1:1
	ds_write2_b32 v39, v144, v145 offset1:1
	ds_write2_b32 v40, v146, v147 offset1:1
	ds_write2_b32 v41, v148, v149 offset1:1
	ds_write2_b32 v42, v150, v151 offset1:1
	ds_write2_b32 v43, v152, v153 offset1:1
	ds_write2_b32 v44, v154, v155 offset1:1
	ds_write2_b32 v45, v156, v157 offset1:1
	ds_write2_b32 v46, v158, v159 offset1:1
	s_waitcnt lgkmcnt(0)
	ds_read2_b32 v[48:49], v31 offset0:0 offset1:8
	ds_read2_b32 v[50:51], v31 offset0:33 offset1:41
	ds_read2_b32 v[52:53], v31 offset0:66 offset1:74
	ds_read2_b32 v[54:55], v31 offset0:99 offset1:107
	ds_read2_b32 v[56:57], v31 offset0:132 offset1:140
	ds_read2_b32 v[58:59], v31 offset0:165 offset1:173
	ds_read2_b32 v[60:61], v31 offset0:198 offset1:206
	ds_read2_b32 v[62:63], v31 offset0:231 offset1:239
	ds_read2_b32 v[64:65], v31 offset0:16 offset1:24
	ds_read2_b32 v[66:67], v31 offset0:49 offset1:57
	ds_read2_b32 v[68:69], v31 offset0:82 offset1:90
	ds_read2_b32 v[70:71], v31 offset0:115 offset1:123
	ds_read2_b32 v[72:73], v31 offset0:148 offset1:156
	ds_read2_b32 v[74:75], v31 offset0:181 offset1:189
	ds_read2_b32 v[76:77], v31 offset0:214 offset1:222
	ds_read2_b32 v[78:79], v31 offset0:247 offset1:255
	s_waitcnt lgkmcnt(8)
; #define GAS __attribute__((address_space(1)))
; #define LAS __attribute__((address_space(3)))
; #define LDS_WAIT() asm volatile("s_waitcnt lgkmcnt(0)" ::: "memory")
; __device__ __forceinline__ void p0_transpose_item(const float* W, int ldw, int src_col0, int k0, bf16_t* WT, int ldk, int dst_row0, int dst_k0, LAS float* scr, int lane) {
; #pragma unroll
;     for (int i = 0; i < 8; ++i) { const int kk = 8 * i + (lane >> 3), n4 = 4 * (lane & 7);
;         const f32x4 w = *(const GAS f32x4*)(W + (size_t)(k0 + kk) * ldw + src_col0 + n4); LAS float* d = scr + kk * 33 + n4; d[0] = w[0]; d[1] = w[1]; d[2] = w[2]; d[3] = w[3]; }
;     LDS_WAIT(); asm volatile("" ::: "memory");
;     const int c = lane & 7;
; #pragma unroll
;     for (int j = 0; j < 4; ++j) { const int n = (lane >> 3) + 8 * j; const LAS float* s = scr + (8 * c) * 33 + n;
;         v4u o; o.x = pk2(s[0 * 33], s[1 * 33]); o.y = pk2(s[2 * 33], s[3 * 33]); o.z = pk2(s[4 * 33], s[5 * 33]); o.w = pk2(s[6 * 33], s[7 * 33]);
;         *(GAS v4u*)(WT + (size_t)(dst_row0 + n) * ldk + dst_k0 + k0 + 8 * c) = o; }
;     LDS_WAIT(); asm volatile("" ::: "memory");
; __global__ void __launch_bounds__(NWAVES * 64, 2) fwd(Args args) {
;     ...
;                 if (blockIdx.x < 64) for (int it = ((int)blockIdx.x - 32) * NWAVES + wave; it < I_BA + I_BB + I_O + I_UP + I_DN; it += 32 * NWAVES) {
;                     int r = it;
;                     if (r < I_BA) { const int kb = r / 32, nb = r % 32; p0_transpose_item(wba, 1024, 32 * nb, 64 * kb, WBAB_T, 1024, 32 * nb, 0, scr, lane); continue; } r -= I_BA;
;                     if (r < I_BB) { const int kb = r / 32, nb = r % 32; p0_transpose_item(wbb, 1024, 32 * nb, 64 * kb, WBAB_T, 1024, 32 * nb, 512, scr, lane); continue; } r -= I_BB;
;                     if (r < I_O) { const int kb = r / 32, nb = r % 32; p0_transpose_item(wo, 1024, 32 * nb, 64 * kb, WO_T, 1024, 32 * nb, 0, scr, lane); continue; } r -= I_O;
;                     if (r < I_UP) { const int kb = r / 128, nb = r % 128; p0_transpose_item(wup, FF, 32 * nb, 64 * kb, WUP_T, 1024, 32 * nb, 0, scr, lane); continue; } r -= I_UP;
;                     { const int kb = r / 32, nb = r % 32; p0_transpose_item(wdn, 1024, 32 * nb, 64 * kb, WDN_T, FF, 32 * nb, 0, scr, lane); }
	v_cvt_pk_bf16_f32 v80, v48, v50
	v_cvt_pk_bf16_f32 v81, v52, v54
	v_cvt_pk_bf16_f32 v82, v56, v58
	v_cvt_pk_bf16_f32 v83, v60, v62
	v_cvt_pk_bf16_f32 v84, v49, v51
	v_cvt_pk_bf16_f32 v85, v53, v55
	v_cvt_pk_bf16_f32 v86, v57, v59
	v_cvt_pk_bf16_f32 v87, v61, v63
	s_waitcnt lgkmcnt(0)
	v_cvt_pk_bf16_f32 v88, v64, v66
	v_cvt_pk_bf16_f32 v89, v68, v70
	v_cvt_pk_bf16_f32 v90, v72, v74
	v_cvt_pk_bf16_f32 v91, v76, v78
	v_cvt_pk_bf16_f32 v92, v65, v67
	v_cvt_pk_bf16_f32 v93, v69, v71
	v_cvt_pk_bf16_f32 v94, v73, v75
	v_cvt_pk_bf16_f32 v95, v77, v79
	global_store_dwordx4 v116, v[80:83], s[82:83]
	global_store_dwordx4 v117, v[84:87], s[82:83]
	global_store_dwordx4 v118, v[88:91], s[82:83]
	global_store_dwordx4 v119, v[92:95], s[82:83]
	s_add_u32 s44, s44, 0x200000
	s_addc_u32 s45, s45, 0
	global_load_dwordx4 v[128:131], v100, s[44:45] nt
	global_load_dwordx4 v[132:135], v101, s[44:45] nt
	global_load_dwordx4 v[136:139], v102, s[44:45] nt
	global_load_dwordx4 v[140:143], v103, s[44:45] nt
	global_load_dwordx4 v[144:147], v104, s[44:45] nt
	global_load_dwordx4 v[148:151], v105, s[44:45] nt
	global_load_dwordx4 v[152:155], v106, s[44:45] nt
	global_load_dwordx4 v[156:159], v107, s[44:45] nt
	s_waitcnt vmcnt(16)
	ds_write2_b32 v32, v160, v161 offset1:1
	ds_write2_b32 v32, v162, v163 offset0:2 offset1:3
	ds_write2_b32 v33, v164, v165 offset1:1
	ds_write2_b32 v34, v166, v167 offset1:1
	ds_write2_b32 v35, v168, v169 offset1:1
	ds_write2_b32 v36, v170, v171 offset1:1
	ds_write2_b32 v37, v172, v173 offset1:1
	ds_write2_b32 v38, v174, v175 offset1:1
	ds_write2_b32 v39, v176, v177 offset1:1
	ds_write2_b32 v40, v178, v179 offset1:1
	ds_write2_b32 v41, v180, v181 offset1:1
	ds_write2_b32 v42, v182, v183 offset1:1
	ds_write2_b32 v43, v184, v185 offset1:1
	ds_write2_b32 v44, v186, v187 offset1:1
	ds_write2_b32 v45, v188, v189 offset1:1
	ds_write2_b32 v46, v190, v191 offset1:1
	s_waitcnt lgkmcnt(0)
	ds_read2_b32 v[48:49], v31 offset0:0 offset1:8
	ds_read2_b32 v[50:51], v31 offset0:33 offset1:41
	ds_read2_b32 v[52:53], v31 offset0:66 offset1:74
	ds_read2_b32 v[54:55], v31 offset0:99 offset1:107
	ds_read2_b32 v[56:57], v31 offset0:132 offset1:140
	ds_read2_b32 v[58:59], v31 offset0:165 offset1:173
	ds_read2_b32 v[60:61], v31 offset0:198 offset1:206
	ds_read2_b32 v[62:63], v31 offset0:231 offset1:239
	ds_read2_b32 v[64:65], v31 offset0:16 offset1:24
	ds_read2_b32 v[66:67], v31 offset0:49 offset1:57
	ds_read2_b32 v[68:69], v31 offset0:82 offset1:90
	ds_read2_b32 v[70:71], v31 offset0:115 offset1:123
	ds_read2_b32 v[72:73], v31 offset0:148 offset1:156
	ds_read2_b32 v[74:75], v31 offset0:181 offset1:189
	ds_read2_b32 v[76:77], v31 offset0:214 offset1:222
	ds_read2_b32 v[78:79], v31 offset0:247 offset1:255
	s_waitcnt lgkmcnt(8)
	v_cvt_pk_bf16_f32 v80, v48, v50
	v_cvt_pk_bf16_f32 v81, v52, v54
	v_cvt_pk_bf16_f32 v82, v56, v58
	v_cvt_pk_bf16_f32 v83, v60, v62
	v_cvt_pk_bf16_f32 v84, v49, v51
	v_cvt_pk_bf16_f32 v85, v53, v55
	v_cvt_pk_bf16_f32 v86, v57, v59
	v_cvt_pk_bf16_f32 v87, v61, v63
	s_waitcnt lgkmcnt(0)
	v_cvt_pk_bf16_f32 v88, v64, v66
	v_cvt_pk_bf16_f32 v89, v68, v70
	v_cvt_pk_bf16_f32 v90, v72, v74
	v_cvt_pk_bf16_f32 v91, v76, v78
	v_cvt_pk_bf16_f32 v92, v65, v67
	v_cvt_pk_bf16_f32 v93, v69, v71
	v_cvt_pk_bf16_f32 v94, v73, v75
	v_cvt_pk_bf16_f32 v95, v77, v79
	global_store_dwordx4 v116, v[80:83], s[82:83] offset:1024
	global_store_dwordx4 v117, v[84:87], s[82:83] offset:1024
	global_store_dwordx4 v118, v[88:91], s[82:83] offset:1024
	global_store_dwordx4 v119, v[92:95], s[82:83] offset:1024
	global_load_dwordx4 v[160:163], v108, s[46:47] nt
	global_load_dwordx4 v[164:167], v109, s[46:47] nt
	global_load_dwordx4 v[168:171], v110, s[46:47] nt
	global_load_dwordx4 v[172:175], v111, s[46:47] nt
	global_load_dwordx4 v[176:179], v112, s[46:47] nt
	global_load_dwordx4 v[180:183], v113, s[46:47] nt
	global_load_dwordx4 v[184:187], v114, s[46:47] nt
	global_load_dwordx4 v[188:191], v115, s[46:47] nt
	s_waitcnt vmcnt(16)
	ds_write2_b32 v32, v192, v193 offset1:1
	ds_write2_b32 v32, v194, v195 offset0:2 offset1:3
	ds_write2_b32 v33, v196, v197 offset1:1
	ds_write2_b32 v34, v198, v199 offset1:1
	ds_write2_b32 v35, v200, v201 offset1:1
	ds_write2_b32 v36, v202, v203 offset1:1
	ds_write2_b32 v37, v204, v205 offset1:1
	ds_write2_b32 v38, v206, v207 offset1:1
	ds_write2_b32 v39, v208, v209 offset1:1
	ds_write2_b32 v40, v210, v211 offset1:1
	ds_write2_b32 v41, v212, v213 offset1:1
	ds_write2_b32 v42, v214, v215 offset1:1
	ds_write2_b32 v43, v216, v217 offset1:1
	ds_write2_b32 v44, v218, v219 offset1:1
	ds_write2_b32 v45, v220, v221 offset1:1
	ds_write2_b32 v46, v222, v223 offset1:1
	s_waitcnt lgkmcnt(0)
	ds_read2_b32 v[48:49], v31 offset0:0 offset1:8
	ds_read2_b32 v[50:51], v31 offset0:33 offset1:41
	ds_read2_b32 v[52:53], v31 offset0:66 offset1:74
	ds_read2_b32 v[54:55], v31 offset0:99 offset1:107
	ds_read2_b32 v[56:57], v31 offset0:132 offset1:140
	ds_read2_b32 v[58:59], v31 offset0:165 offset1:173
	ds_read2_b32 v[60:61], v31 offset0:198 offset1:206
	ds_read2_b32 v[62:63], v31 offset0:231 offset1:239
	ds_read2_b32 v[64:65], v31 offset0:16 offset1:24
	ds_read2_b32 v[66:67], v31 offset0:49 offset1:57
	ds_read2_b32 v[68:69], v31 offset0:82 offset1:90
	ds_read2_b32 v[70:71], v31 offset0:115 offset1:123
	ds_read2_b32 v[72:73], v31 offset0:148 offset1:156
	ds_read2_b32 v[74:75], v31 offset0:181 offset1:189
	ds_read2_b32 v[76:77], v31 offset0:214 offset1:222
	ds_read2_b32 v[78:79], v31 offset0:247 offset1:255
	s_waitcnt lgkmcnt(8)
	v_cvt_pk_bf16_f32 v80, v48, v50
	v_cvt_pk_bf16_f32 v81, v52, v54
	v_cvt_pk_bf16_f32 v82, v56, v58
	v_cvt_pk_bf16_f32 v83, v60, v62
	v_cvt_pk_bf16_f32 v84, v49, v51
	v_cvt_pk_bf16_f32 v85, v53, v55
	v_cvt_pk_bf16_f32 v86, v57, v59
	v_cvt_pk_bf16_f32 v87, v61, v63
	s_waitcnt lgkmcnt(0)
; #define GAS __attribute__((address_space(1)))
; #define LAS __attribute__((address_space(3)))
; #define LDS_WAIT() asm volatile("s_waitcnt lgkmcnt(0)" ::: "memory")
; __device__ __forceinline__ unsigned pk2(float lo, float hi) { const f32x2_t v = {lo, hi}; return __builtin_bit_cast(unsigned, __builtin_convertvector(v, bf16x2_t)); }
; __device__ __forceinline__ void p0_transpose_item(const float* W, int ldw, int src_col0, int k0, bf16_t* WT, int ldk, int dst_row0, int dst_k0, LAS float* scr, int lane) {
; #pragma unroll
;     for (int i = 0; i < 8; ++i) { const int kk = 8 * i + (lane >> 3), n4 = 4 * (lane & 7);
;         const f32x4 w = *(const GAS f32x4*)(W + (size_t)(k0 + kk) * ldw + src_col0 + n4); LAS float* d = scr + kk * 33 + n4; d[0] = w[0]; d[1] = w[1]; d[2] = w[2]; d[3] = w[3]; }
;     LDS_WAIT(); asm volatile("" ::: "memory");
;     const int c = lane & 7;
; #pragma unroll
;     for (int j = 0; j < 4; ++j) { const int n = (lane >> 3) + 8 * j; const LAS float* s = scr + (8 * c) * 33 + n;
;         v4u o; o.x = pk2(s[0 * 33], s[1 * 33]); o.y = pk2(s[2 * 33], s[3 * 33]); o.z = pk2(s[4 * 33], s[5 * 33]); o.w = pk2(s[6 * 33], s[7 * 33]);
;         *(GAS v4u*)(WT + (size_t)(dst_row0 + n) * ldk + dst_k0 + k0 + 8 * c) = o; }
;     LDS_WAIT(); asm volatile("" ::: "memory");
; __global__ void __launch_bounds__(NWAVES * 64, 2) fwd(Args args) {
;     ...
;                 if (blockIdx.x < 64) for (int it = ((int)blockIdx.x - 32) * NWAVES + wave; it < I_BA + I_BB + I_O + I_UP + I_DN; it += 32 * NWAVES) {
;                     int r = it;
;                     if (r < I_BA) { const int kb = r / 32, nb = r % 32; p0_transpose_item(wba, 1024, 32 * nb, 64 * kb, WBAB_T, 1024, 32 * nb, 0, scr, lane); continue; } r -= I_BA;
;                     if (r < I_BB) { const int kb = r / 32, nb = r % 32; p0_transpose_item(wbb, 1024, 32 * nb, 64 * kb, WBAB_T, 1024, 32 * nb, 512, scr, lane); continue; } r -= I_BB;
;                     if (r < I_O) { const int kb = r / 32, nb = r % 32; p0_transpose_item(wo, 1024, 32 * nb, 64 * kb, WO_T, 1024, 32 * nb, 0, scr, lane); continue; } r -= I_O;
;                     if (r < I_UP) { const int kb = r / 128, nb = r % 128; p0_transpose_item(wup, FF, 32 * nb, 64 * kb, WUP_T, 1024, 32 * nb, 0, scr, lane); continue; } r -= I_UP;
	v_cvt_pk_bf16_f32 v88, v64, v66
	v_cvt_pk_bf16_f32 v89, v68, v70
	v_cvt_pk_bf16_f32 v90, v72, v74
	v_cvt_pk_bf16_f32 v91, v76, v78
	v_cvt_pk_bf16_f32 v92, v65, v67
	v_cvt_pk_bf16_f32 v93, v69, v71
	v_cvt_pk_bf16_f32 v94, v73, v75
	v_cvt_pk_bf16_f32 v95, v77, v79
	global_store_dwordx4 v116, v[80:83], s[84:85]
	global_store_dwordx4 v117, v[84:87], s[84:85]
	global_store_dwordx4 v118, v[88:91], s[84:85]
	global_store_dwordx4 v119, v[92:95], s[84:85]
	s_add_u32 s46, s46, 0x200000
	s_addc_u32 s47, s47, 0
	global_load_dwordx4 v[192:195], v108, s[46:47] nt
	global_load_dwordx4 v[196:199], v109, s[46:47] nt
	global_load_dwordx4 v[200:203], v110, s[46:47] nt
	global_load_dwordx4 v[204:207], v111, s[46:47] nt
	global_load_dwordx4 v[208:211], v112, s[46:47] nt
	global_load_dwordx4 v[212:215], v113, s[46:47] nt
	global_load_dwordx4 v[216:219], v114, s[46:47] nt
	global_load_dwordx4 v[220:223], v115, s[46:47] nt
	s_waitcnt vmcnt(16)
	ds_write2_b32 v32, v128, v129 offset1:1
	ds_write2_b32 v32, v130, v131 offset0:2 offset1:3
	ds_write2_b32 v33, v132, v133 offset1:1
	ds_write2_b32 v34, v134, v135 offset1:1
	ds_write2_b32 v35, v136, v137 offset1:1
	ds_write2_b32 v36, v138, v139 offset1:1
	ds_write2_b32 v37, v140, v141 offset1:1
	ds_write2_b32 v38, v142, v143 offset1:1
	ds_write2_b32 v39, v144, v145 offset1:1
	ds_write2_b32 v40, v146, v147 offset1:1
	ds_write2_b32 v41, v148, v149 offset1:1
	ds_write2_b32 v42, v150, v151 offset1:1
	ds_write2_b32 v43, v152, v153 offset1:1
	ds_write2_b32 v44, v154, v155 offset1:1
	ds_write2_b32 v45, v156, v157 offset1:1
	ds_write2_b32 v46, v158, v159 offset1:1
	s_waitcnt lgkmcnt(0)
	ds_read2_b32 v[48:49], v31 offset0:0 offset1:8
	ds_read2_b32 v[50:51], v31 offset0:33 offset1:41
	ds_read2_b32 v[52:53], v31 offset0:66 offset1:74
	ds_read2_b32 v[54:55], v31 offset0:99 offset1:107
	ds_read2_b32 v[56:57], v31 offset0:132 offset1:140
	ds_read2_b32 v[58:59], v31 offset0:165 offset1:173
	ds_read2_b32 v[60:61], v31 offset0:198 offset1:206
	ds_read2_b32 v[62:63], v31 offset0:231 offset1:239
	ds_read2_b32 v[64:65], v31 offset0:16 offset1:24
	ds_read2_b32 v[66:67], v31 offset0:49 offset1:57
	ds_read2_b32 v[68:69], v31 offset0:82 offset1:90
	ds_read2_b32 v[70:71], v31 offset0:115 offset1:123
	ds_read2_b32 v[72:73], v31 offset0:148 offset1:156
	ds_read2_b32 v[74:75], v31 offset0:181 offset1:189
	ds_read2_b32 v[76:77], v31 offset0:214 offset1:222
	ds_read2_b32 v[78:79], v31 offset0:247 offset1:255
	s_waitcnt lgkmcnt(8)
	v_cvt_pk_bf16_f32 v80, v48, v50
	v_cvt_pk_bf16_f32 v81, v52, v54
	v_cvt_pk_bf16_f32 v82, v56, v58
	v_cvt_pk_bf16_f32 v83, v60, v62
	v_cvt_pk_bf16_f32 v84, v49, v51
	v_cvt_pk_bf16_f32 v85, v53, v55
	v_cvt_pk_bf16_f32 v86, v57, v59
	v_cvt_pk_bf16_f32 v87, v61, v63
	s_waitcnt lgkmcnt(0)
	v_cvt_pk_bf16_f32 v88, v64, v66
	v_cvt_pk_bf16_f32 v89, v68, v70
	v_cvt_pk_bf16_f32 v90, v72, v74
	v_cvt_pk_bf16_f32 v91, v76, v78
	v_cvt_pk_bf16_f32 v92, v65, v67
	v_cvt_pk_bf16_f32 v93, v69, v71
	v_cvt_pk_bf16_f32 v94, v73, v75
	v_cvt_pk_bf16_f32 v95, v77, v79
	global_store_dwordx4 v116, v[80:83], s[84:85] offset:1024
	global_store_dwordx4 v117, v[84:87], s[84:85] offset:1024
	global_store_dwordx4 v118, v[88:91], s[84:85] offset:1024
	global_store_dwordx4 v119, v[92:95], s[84:85] offset:1024
	s_add_u32 s46, s46, 0x200000
	s_addc_u32 s47, s47, 0
	global_load_dwordx4 v[128:131], v108, s[46:47] nt
	global_load_dwordx4 v[132:135], v109, s[46:47] nt
	global_load_dwordx4 v[136:139], v110, s[46:47] nt
	global_load_dwordx4 v[140:143], v111, s[46:47] nt
	global_load_dwordx4 v[144:147], v112, s[46:47] nt
	global_load_dwordx4 v[148:151], v113, s[46:47] nt
	global_load_dwordx4 v[152:155], v114, s[46:47] nt
	global_load_dwordx4 v[156:159], v115, s[46:47] nt
	s_waitcnt vmcnt(16)
	ds_write2_b32 v32, v160, v161 offset1:1
	ds_write2_b32 v32, v162, v163 offset0:2 offset1:3
	ds_write2_b32 v33, v164, v165 offset1:1
	ds_write2_b32 v34, v166, v167 offset1:1
	ds_write2_b32 v35, v168, v169 offset1:1
	ds_write2_b32 v36, v170, v171 offset1:1
	ds_write2_b32 v37, v172, v173 offset1:1
	ds_write2_b32 v38, v174, v175 offset1:1
	ds_write2_b32 v39, v176, v177 offset1:1
	ds_write2_b32 v40, v178, v179 offset1:1
	ds_write2_b32 v41, v180, v181 offset1:1
	ds_write2_b32 v42, v182, v183 offset1:1
	ds_write2_b32 v43, v184, v185 offset1:1
	ds_write2_b32 v44, v186, v187 offset1:1
	ds_write2_b32 v45, v188, v189 offset1:1
	ds_write2_b32 v46, v190, v191 offset1:1
	s_waitcnt lgkmcnt(0)
	ds_read2_b32 v[48:49], v31 offset0:0 offset1:8
	ds_read2_b32 v[50:51], v31 offset0:33 offset1:41
	ds_read2_b32 v[52:53], v31 offset0:66 offset1:74
	ds_read2_b32 v[54:55], v31 offset0:99 offset1:107
	ds_read2_b32 v[56:57], v31 offset0:132 offset1:140
	ds_read2_b32 v[58:59], v31 offset0:165 offset1:173
	ds_read2_b32 v[60:61], v31 offset0:198 offset1:206
	ds_read2_b32 v[62:63], v31 offset0:231 offset1:239
	ds_read2_b32 v[64:65], v31 offset0:16 offset1:24
	ds_read2_b32 v[66:67], v31 offset0:49 offset1:57
	ds_read2_b32 v[68:69], v31 offset0:82 offset1:90
	ds_read2_b32 v[70:71], v31 offset0:115 offset1:123
	ds_read2_b32 v[72:73], v31 offset0:148 offset1:156
	ds_read2_b32 v[74:75], v31 offset0:181 offset1:189
	ds_read2_b32 v[76:77], v31 offset0:214 offset1:222
	ds_read2_b32 v[78:79], v31 offset0:247 offset1:255
	s_waitcnt lgkmcnt(8)
	v_cvt_pk_bf16_f32 v80, v48, v50
	v_cvt_pk_bf16_f32 v81, v52, v54
	v_cvt_pk_bf16_f32 v82, v56, v58
	v_cvt_pk_bf16_f32 v83, v60, v62
	v_cvt_pk_bf16_f32 v84, v49, v51
	v_cvt_pk_bf16_f32 v85, v53, v55
	v_cvt_pk_bf16_f32 v86, v57, v59
	v_cvt_pk_bf16_f32 v87, v61, v63
	s_waitcnt lgkmcnt(0)
; #define GAS __attribute__((address_space(1)))
; #define LAS __attribute__((address_space(3)))
; #define LDS_WAIT() asm volatile("s_waitcnt lgkmcnt(0)" ::: "memory")
; __device__ __forceinline__ unsigned pk2(float lo, float hi) { const f32x2_t v = {lo, hi}; return __builtin_bit_cast(unsigned, __builtin_convertvector(v, bf16x2_t)); }
; __device__ __forceinline__ void p0_transpose_item(const float* W, int ldw, int src_col0, int k0, bf16_t* WT, int ldk, int dst_row0, int dst_k0, LAS float* scr, int lane) {
; #pragma unroll
;     for (int i = 0; i < 8; ++i) { const int kk = 8 * i + (lane >> 3), n4 = 4 * (lane & 7);
;         const f32x4 w = *(const GAS f32x4*)(W + (size_t)(k0 + kk) * ldw + src_col0 + n4); LAS float* d = scr + kk * 33 + n4; d[0] = w[0]; d[1] = w[1]; d[2] = w[2]; d[3] = w[3]; }
;     LDS_WAIT(); asm volatile("" ::: "memory");
;     const int c = lane & 7;
; #pragma unroll
;     for (int j = 0; j < 4; ++j) { const int n = (lane >> 3) + 8 * j; const LAS float* s = scr + (8 * c) * 33 + n;
;         v4u o; o.x = pk2(s[0 * 33], s[1 * 33]); o.y = pk2(s[2 * 33], s[3 * 33]); o.z = pk2(s[4 * 33], s[5 * 33]); o.w = pk2(s[6 * 33], s[7 * 33]);
;         *(GAS v4u*)(WT + (size_t)(dst_row0 + n) * ldk + dst_k0 + k0 + 8 * c) = o; }
;     LDS_WAIT(); asm volatile("" ::: "memory");
; __global__ void __launch_bounds__(NWAVES * 64, 2) fwd(Args args) {
;     ...
;                 if (blockIdx.x < 64) for (int it = ((int)blockIdx.x - 32) * NWAVES + wave; it < I_BA + I_BB + I_O + I_UP + I_DN; it += 32 * NWAVES) {
;                     int r = it;
;                     if (r < I_BA) { const int kb = r / 32, nb = r % 32; p0_transpose_item(wba, 1024, 32 * nb, 64 * kb, WBAB_T, 1024, 32 * nb, 0, scr, lane); continue; } r -= I_BA;
;                     if (r < I_BB) { const int kb = r / 32, nb = r % 32; p0_transpose_item(wbb, 1024, 32 * nb, 64 * kb, WBAB_T, 1024, 32 * nb, 512, scr, lane); continue; } r -= I_BB;
;                     if (r < I_O) { const int kb = r / 32, nb = r % 32; p0_transpose_item(wo, 1024, 32 * nb, 64 * kb, WO_T, 1024, 32 * nb, 0, scr, lane); continue; } r -= I_O;
;                     if (r < I_UP) { const int kb = r / 128, nb = r % 128; p0_transpose_item(wup, FF, 32 * nb, 64 * kb, WUP_T, 1024, 32 * nb, 0, scr, lane); continue; } r -= I_UP;
	v_cvt_pk_bf16_f32 v88, v64, v66
	v_cvt_pk_bf16_f32 v89, v68, v70
	v_cvt_pk_bf16_f32 v90, v72, v74
	v_cvt_pk_bf16_f32 v91, v76, v78
	v_cvt_pk_bf16_f32 v92, v65, v67
	v_cvt_pk_bf16_f32 v93, v69, v71
	v_cvt_pk_bf16_f32 v94, v73, v75
	v_cvt_pk_bf16_f32 v95, v77, v79
	global_store_dwordx4 v116, v[80:83], s[86:87]
	global_store_dwordx4 v117, v[84:87], s[86:87]
	global_store_dwordx4 v118, v[88:91], s[86:87]
	global_store_dwordx4 v119, v[92:95], s[86:87]
	s_add_u32 s46, s46, 0x200000
	s_addc_u32 s47, s47, 0
	global_load_dwordx4 v[160:163], v108, s[46:47] nt
	global_load_dwordx4 v[164:167], v109, s[46:47] nt
	global_load_dwordx4 v[168:171], v110, s[46:47] nt
	global_load_dwordx4 v[172:175], v111, s[46:47] nt
	global_load_dwordx4 v[176:179], v112, s[46:47] nt
	global_load_dwordx4 v[180:183], v113, s[46:47] nt
	global_load_dwordx4 v[184:187], v114, s[46:47] nt
	global_load_dwordx4 v[188:191], v115, s[46:47] nt
	s_waitcnt vmcnt(16)
	ds_write2_b32 v32, v192, v193 offset1:1
	ds_write2_b32 v32, v194, v195 offset0:2 offset1:3
	ds_write2_b32 v33, v196, v197 offset1:1
	ds_write2_b32 v34, v198, v199 offset1:1
	ds_write2_b32 v35, v200, v201 offset1:1
	ds_write2_b32 v36, v202, v203 offset1:1
	ds_write2_b32 v37, v204, v205 offset1:1
	ds_write2_b32 v38, v206, v207 offset1:1
	ds_write2_b32 v39, v208, v209 offset1:1
	ds_write2_b32 v40, v210, v211 offset1:1
	ds_write2_b32 v41, v212, v213 offset1:1
	ds_write2_b32 v42, v214, v215 offset1:1
	ds_write2_b32 v43, v216, v217 offset1:1
	ds_write2_b32 v44, v218, v219 offset1:1
	ds_write2_b32 v45, v220, v221 offset1:1
	ds_write2_b32 v46, v222, v223 offset1:1
	s_waitcnt lgkmcnt(0)
	ds_read2_b32 v[48:49], v31 offset0:0 offset1:8
	ds_read2_b32 v[50:51], v31 offset0:33 offset1:41
	ds_read2_b32 v[52:53], v31 offset0:66 offset1:74
	ds_read2_b32 v[54:55], v31 offset0:99 offset1:107
	ds_read2_b32 v[56:57], v31 offset0:132 offset1:140
	ds_read2_b32 v[58:59], v31 offset0:165 offset1:173
	ds_read2_b32 v[60:61], v31 offset0:198 offset1:206
	ds_read2_b32 v[62:63], v31 offset0:231 offset1:239
	ds_read2_b32 v[64:65], v31 offset0:16 offset1:24
	ds_read2_b32 v[66:67], v31 offset0:49 offset1:57
	ds_read2_b32 v[68:69], v31 offset0:82 offset1:90
	ds_read2_b32 v[70:71], v31 offset0:115 offset1:123
	ds_read2_b32 v[72:73], v31 offset0:148 offset1:156
	ds_read2_b32 v[74:75], v31 offset0:181 offset1:189
	ds_read2_b32 v[76:77], v31 offset0:214 offset1:222
	ds_read2_b32 v[78:79], v31 offset0:247 offset1:255
	s_waitcnt lgkmcnt(8)
	v_cvt_pk_bf16_f32 v80, v48, v50
	v_cvt_pk_bf16_f32 v81, v52, v54
	v_cvt_pk_bf16_f32 v82, v56, v58
	v_cvt_pk_bf16_f32 v83, v60, v62
	v_cvt_pk_bf16_f32 v84, v49, v51
	v_cvt_pk_bf16_f32 v85, v53, v55
	v_cvt_pk_bf16_f32 v86, v57, v59
	v_cvt_pk_bf16_f32 v87, v61, v63
	s_waitcnt lgkmcnt(0)
	v_cvt_pk_bf16_f32 v88, v64, v66
	v_cvt_pk_bf16_f32 v89, v68, v70
	v_cvt_pk_bf16_f32 v90, v72, v74
	v_cvt_pk_bf16_f32 v91, v76, v78
	v_cvt_pk_bf16_f32 v92, v65, v67
	v_cvt_pk_bf16_f32 v93, v69, v71
	v_cvt_pk_bf16_f32 v94, v73, v75
	v_cvt_pk_bf16_f32 v95, v77, v79
	global_store_dwordx4 v116, v[80:83], s[86:87] offset:256
	global_store_dwordx4 v117, v[84:87], s[86:87] offset:256
	global_store_dwordx4 v118, v[88:91], s[86:87] offset:256
	global_store_dwordx4 v119, v[92:95], s[86:87] offset:256
	s_add_u32 s46, s46, 0x200000
	s_addc_u32 s47, s47, 0
	global_load_dwordx4 v[192:195], v108, s[46:47] nt
	global_load_dwordx4 v[196:199], v109, s[46:47] nt
	global_load_dwordx4 v[200:203], v110, s[46:47] nt
	global_load_dwordx4 v[204:207], v111, s[46:47] nt
	global_load_dwordx4 v[208:211], v112, s[46:47] nt
	global_load_dwordx4 v[212:215], v113, s[46:47] nt
	global_load_dwordx4 v[216:219], v114, s[46:47] nt
	global_load_dwordx4 v[220:223], v115, s[46:47] nt
	s_waitcnt vmcnt(16)
	ds_write2_b32 v32, v128, v129 offset1:1
	ds_write2_b32 v32, v130, v131 offset0:2 offset1:3
	ds_write2_b32 v33, v132, v133 offset1:1
	ds_write2_b32 v34, v134, v135 offset1:1
	ds_write2_b32 v35, v136, v137 offset1:1
	ds_write2_b32 v36, v138, v139 offset1:1
	ds_write2_b32 v37, v140, v141 offset1:1
	ds_write2_b32 v38, v142, v143 offset1:1
	ds_write2_b32 v39, v144, v145 offset1:1
	ds_write2_b32 v40, v146, v147 offset1:1
	ds_write2_b32 v41, v148, v149 offset1:1
	ds_write2_b32 v42, v150, v151 offset1:1
	ds_write2_b32 v43, v152, v153 offset1:1
	ds_write2_b32 v44, v154, v155 offset1:1
	ds_write2_b32 v45, v156, v157 offset1:1
	ds_write2_b32 v46, v158, v159 offset1:1
	s_waitcnt lgkmcnt(0)
	ds_read2_b32 v[48:49], v31 offset0:0 offset1:8
	ds_read2_b32 v[50:51], v31 offset0:33 offset1:41
	ds_read2_b32 v[52:53], v31 offset0:66 offset1:74
	ds_read2_b32 v[54:55], v31 offset0:99 offset1:107
	ds_read2_b32 v[56:57], v31 offset0:132 offset1:140
	ds_read2_b32 v[58:59], v31 offset0:165 offset1:173
	ds_read2_b32 v[60:61], v31 offset0:198 offset1:206
	ds_read2_b32 v[62:63], v31 offset0:231 offset1:239
	ds_read2_b32 v[64:65], v31 offset0:16 offset1:24
	ds_read2_b32 v[66:67], v31 offset0:49 offset1:57
	ds_read2_b32 v[68:69], v31 offset0:82 offset1:90
	ds_read2_b32 v[70:71], v31 offset0:115 offset1:123
	ds_read2_b32 v[72:73], v31 offset0:148 offset1:156
	ds_read2_b32 v[74:75], v31 offset0:181 offset1:189
	ds_read2_b32 v[76:77], v31 offset0:214 offset1:222
	ds_read2_b32 v[78:79], v31 offset0:247 offset1:255
	s_waitcnt lgkmcnt(8)
	v_cvt_pk_bf16_f32 v80, v48, v50
	v_cvt_pk_bf16_f32 v81, v52, v54
	v_cvt_pk_bf16_f32 v82, v56, v58
	v_cvt_pk_bf16_f32 v83, v60, v62
	v_cvt_pk_bf16_f32 v84, v49, v51
	v_cvt_pk_bf16_f32 v85, v53, v55
	v_cvt_pk_bf16_f32 v86, v57, v59
	v_cvt_pk_bf16_f32 v87, v61, v63
	s_waitcnt lgkmcnt(0)
; #define GAS __attribute__((address_space(1)))
; #define LAS __attribute__((address_space(3)))
; #define LDS_WAIT() asm volatile("s_waitcnt lgkmcnt(0)" ::: "memory")
; __device__ __forceinline__ unsigned pk2(float lo, float hi) { const f32x2_t v = {lo, hi}; return __builtin_bit_cast(unsigned, __builtin_convertvector(v, bf16x2_t)); }
; __device__ __forceinline__ void p0_transpose_item(const float* W, int ldw, int src_col0, int k0, bf16_t* WT, int ldk, int dst_row0, int dst_k0, LAS float* scr, int lane) {
; #pragma unroll
;     for (int i = 0; i < 8; ++i) { const int kk = 8 * i + (lane >> 3), n4 = 4 * (lane & 7);
;         const f32x4 w = *(const GAS f32x4*)(W + (size_t)(k0 + kk) * ldw + src_col0 + n4); LAS float* d = scr + kk * 33 + n4; d[0] = w[0]; d[1] = w[1]; d[2] = w[2]; d[3] = w[3]; }
;     LDS_WAIT(); asm volatile("" ::: "memory");
;     const int c = lane & 7;
; #pragma unroll
;     for (int j = 0; j < 4; ++j) { const int n = (lane >> 3) + 8 * j; const LAS float* s = scr + (8 * c) * 33 + n;
;         v4u o; o.x = pk2(s[0 * 33], s[1 * 33]); o.y = pk2(s[2 * 33], s[3 * 33]); o.z = pk2(s[4 * 33], s[5 * 33]); o.w = pk2(s[6 * 33], s[7 * 33]);
;         *(GAS v4u*)(WT + (size_t)(dst_row0 + n) * ldk + dst_k0 + k0 + 8 * c) = o; }
;     LDS_WAIT(); asm volatile("" ::: "memory");
; __global__ void __launch_bounds__(NWAVES * 64, 2) fwd(Args args) {
;     ...
;                 if (blockIdx.x < 64) for (int it = ((int)blockIdx.x - 32) * NWAVES + wave; it < I_BA + I_BB + I_O + I_UP + I_DN; it += 32 * NWAVES) {
;                     int r = it;
;                     if (r < I_BA) { const int kb = r / 32, nb = r % 32; p0_transpose_item(wba, 1024, 32 * nb, 64 * kb, WBAB_T, 1024, 32 * nb, 0, scr, lane); continue; } r -= I_BA;
;                     if (r < I_BB) { const int kb = r / 32, nb = r % 32; p0_transpose_item(wbb, 1024, 32 * nb, 64 * kb, WBAB_T, 1024, 32 * nb, 512, scr, lane); continue; } r -= I_BB;
;                     if (r < I_O) { const int kb = r / 32, nb = r % 32; p0_transpose_item(wo, 1024, 32 * nb, 64 * kb, WO_T, 1024, 32 * nb, 0, scr, lane); continue; } r -= I_O;
;                     if (r < I_UP) { const int kb = r / 128, nb = r % 128; p0_transpose_item(wup, FF, 32 * nb, 64 * kb, WUP_T, 1024, 32 * nb, 0, scr, lane); continue; } r -= I_UP;
	v_cvt_pk_bf16_f32 v88, v64, v66
	v_cvt_pk_bf16_f32 v89, v68, v70
	v_cvt_pk_bf16_f32 v90, v72, v74
	v_cvt_pk_bf16_f32 v91, v76, v78
	v_cvt_pk_bf16_f32 v92, v65, v67
	v_cvt_pk_bf16_f32 v93, v69, v71
	v_cvt_pk_bf16_f32 v94, v73, v75
	v_cvt_pk_bf16_f32 v95, v77, v79
	global_store_dwordx4 v116, v[80:83], s[86:87] offset:512
	global_store_dwordx4 v117, v[84:87], s[86:87] offset:512
	global_store_dwordx4 v118, v[88:91], s[86:87] offset:512
	global_store_dwordx4 v119, v[92:95], s[86:87] offset:512
	s_add_u32 s46, s46, 0x200000
	s_addc_u32 s47, s47, 0
	global_load_dwordx4 v[128:131], v108, s[46:47] nt
	global_load_dwordx4 v[132:135], v109, s[46:47] nt
	global_load_dwordx4 v[136:139], v110, s[46:47] nt
	global_load_dwordx4 v[140:143], v111, s[46:47] nt
	global_load_dwordx4 v[144:147], v112, s[46:47] nt
	global_load_dwordx4 v[148:151], v113, s[46:47] nt
	global_load_dwordx4 v[152:155], v114, s[46:47] nt
	global_load_dwordx4 v[156:159], v115, s[46:47] nt
	s_waitcnt vmcnt(16)
	ds_write2_b32 v32, v160, v161 offset1:1
	ds_write2_b32 v32, v162, v163 offset0:2 offset1:3
	ds_write2_b32 v33, v164, v165 offset1:1
	ds_write2_b32 v34, v166, v167 offset1:1
	ds_write2_b32 v35, v168, v169 offset1:1
	ds_write2_b32 v36, v170, v171 offset1:1
	ds_write2_b32 v37, v172, v173 offset1:1
	ds_write2_b32 v38, v174, v175 offset1:1
	ds_write2_b32 v39, v176, v177 offset1:1
	ds_write2_b32 v40, v178, v179 offset1:1
	ds_write2_b32 v41, v180, v181 offset1:1
	ds_write2_b32 v42, v182, v183 offset1:1
	ds_write2_b32 v43, v184, v185 offset1:1
	ds_write2_b32 v44, v186, v187 offset1:1
	ds_write2_b32 v45, v188, v189 offset1:1
	ds_write2_b32 v46, v190, v191 offset1:1
	s_waitcnt lgkmcnt(0)
	ds_read2_b32 v[48:49], v31 offset0:0 offset1:8
	ds_read2_b32 v[50:51], v31 offset0:33 offset1:41
	ds_read2_b32 v[52:53], v31 offset0:66 offset1:74
	ds_read2_b32 v[54:55], v31 offset0:99 offset1:107
	ds_read2_b32 v[56:57], v31 offset0:132 offset1:140
	ds_read2_b32 v[58:59], v31 offset0:165 offset1:173
	ds_read2_b32 v[60:61], v31 offset0:198 offset1:206
	ds_read2_b32 v[62:63], v31 offset0:231 offset1:239
	ds_read2_b32 v[64:65], v31 offset0:16 offset1:24
	ds_read2_b32 v[66:67], v31 offset0:49 offset1:57
	ds_read2_b32 v[68:69], v31 offset0:82 offset1:90
	ds_read2_b32 v[70:71], v31 offset0:115 offset1:123
	ds_read2_b32 v[72:73], v31 offset0:148 offset1:156
	ds_read2_b32 v[74:75], v31 offset0:181 offset1:189
	ds_read2_b32 v[76:77], v31 offset0:214 offset1:222
	ds_read2_b32 v[78:79], v31 offset0:247 offset1:255
	s_waitcnt lgkmcnt(8)
	v_cvt_pk_bf16_f32 v80, v48, v50
	v_cvt_pk_bf16_f32 v81, v52, v54
	v_cvt_pk_bf16_f32 v82, v56, v58
	v_cvt_pk_bf16_f32 v83, v60, v62
	v_cvt_pk_bf16_f32 v84, v49, v51
	v_cvt_pk_bf16_f32 v85, v53, v55
	v_cvt_pk_bf16_f32 v86, v57, v59
	v_cvt_pk_bf16_f32 v87, v61, v63
	s_waitcnt lgkmcnt(0)
	v_cvt_pk_bf16_f32 v88, v64, v66
	v_cvt_pk_bf16_f32 v89, v68, v70
	v_cvt_pk_bf16_f32 v90, v72, v74
	v_cvt_pk_bf16_f32 v91, v76, v78
	v_cvt_pk_bf16_f32 v92, v65, v67
	v_cvt_pk_bf16_f32 v93, v69, v71
	v_cvt_pk_bf16_f32 v94, v73, v75
	v_cvt_pk_bf16_f32 v95, v77, v79
	global_store_dwordx4 v116, v[80:83], s[86:87] offset:768
	global_store_dwordx4 v117, v[84:87], s[86:87] offset:768
	global_store_dwordx4 v118, v[88:91], s[86:87] offset:768
	global_store_dwordx4 v119, v[92:95], s[86:87] offset:768
	s_add_u32 s46, s46, 0x200000
	s_addc_u32 s47, s47, 0
	global_load_dwordx4 v[160:163], v108, s[46:47] nt
	global_load_dwordx4 v[164:167], v109, s[46:47] nt
	global_load_dwordx4 v[168:171], v110, s[46:47] nt
	global_load_dwordx4 v[172:175], v111, s[46:47] nt
	global_load_dwordx4 v[176:179], v112, s[46:47] nt
	global_load_dwordx4 v[180:183], v113, s[46:47] nt
	global_load_dwordx4 v[184:187], v114, s[46:47] nt
	global_load_dwordx4 v[188:191], v115, s[46:47] nt
	s_waitcnt vmcnt(16)
	ds_write2_b32 v32, v192, v193 offset1:1
	ds_write2_b32 v32, v194, v195 offset0:2 offset1:3
	ds_write2_b32 v33, v196, v197 offset1:1
	ds_write2_b32 v34, v198, v199 offset1:1
	ds_write2_b32 v35, v200, v201 offset1:1
	ds_write2_b32 v36, v202, v203 offset1:1
	ds_write2_b32 v37, v204, v205 offset1:1
	ds_write2_b32 v38, v206, v207 offset1:1
	ds_write2_b32 v39, v208, v209 offset1:1
	ds_write2_b32 v40, v210, v211 offset1:1
	ds_write2_b32 v41, v212, v213 offset1:1
	ds_write2_b32 v42, v214, v215 offset1:1
	ds_write2_b32 v43, v216, v217 offset1:1
	ds_write2_b32 v44, v218, v219 offset1:1
	ds_write2_b32 v45, v220, v221 offset1:1
	ds_write2_b32 v46, v222, v223 offset1:1
	s_waitcnt lgkmcnt(0)
	ds_read2_b32 v[48:49], v31 offset0:0 offset1:8
	ds_read2_b32 v[50:51], v31 offset0:33 offset1:41
	ds_read2_b32 v[52:53], v31 offset0:66 offset1:74
	ds_read2_b32 v[54:55], v31 offset0:99 offset1:107
	ds_read2_b32 v[56:57], v31 offset0:132 offset1:140
	ds_read2_b32 v[58:59], v31 offset0:165 offset1:173
	ds_read2_b32 v[60:61], v31 offset0:198 offset1:206
	ds_read2_b32 v[62:63], v31 offset0:231 offset1:239
	ds_read2_b32 v[64:65], v31 offset0:16 offset1:24
	ds_read2_b32 v[66:67], v31 offset0:49 offset1:57
	ds_read2_b32 v[68:69], v31 offset0:82 offset1:90
	ds_read2_b32 v[70:71], v31 offset0:115 offset1:123
	ds_read2_b32 v[72:73], v31 offset0:148 offset1:156
	ds_read2_b32 v[74:75], v31 offset0:181 offset1:189
	ds_read2_b32 v[76:77], v31 offset0:214 offset1:222
	ds_read2_b32 v[78:79], v31 offset0:247 offset1:255
	s_waitcnt lgkmcnt(8)
	v_cvt_pk_bf16_f32 v80, v48, v50
	v_cvt_pk_bf16_f32 v81, v52, v54
	v_cvt_pk_bf16_f32 v82, v56, v58
	v_cvt_pk_bf16_f32 v83, v60, v62
	v_cvt_pk_bf16_f32 v84, v49, v51
	v_cvt_pk_bf16_f32 v85, v53, v55
	v_cvt_pk_bf16_f32 v86, v57, v59
	v_cvt_pk_bf16_f32 v87, v61, v63
	s_waitcnt lgkmcnt(0)
; #define GAS __attribute__((address_space(1)))
; #define LAS __attribute__((address_space(3)))
; #define LDS_WAIT() asm volatile("s_waitcnt lgkmcnt(0)" ::: "memory")
; __device__ __forceinline__ void p0_transpose_item(const float* W, int ldw, int src_col0, int k0, bf16_t* WT, int ldk, int dst_row0, int dst_k0, LAS float* scr, int lane) {
; #pragma unroll
;     for (int i = 0; i < 8; ++i) { const int kk = 8 * i + (lane >> 3), n4 = 4 * (lane & 7);
;         const f32x4 w = *(const GAS f32x4*)(W + (size_t)(k0 + kk) * ldw + src_col0 + n4); LAS float* d = scr + kk * 33 + n4; d[0] = w[0]; d[1] = w[1]; d[2] = w[2]; d[3] = w[3]; }
;     LDS_WAIT(); asm volatile("" ::: "memory");
;     const int c = lane & 7;
; #pragma unroll
;     for (int j = 0; j < 4; ++j) { const int n = (lane >> 3) + 8 * j; const LAS float* s = scr + (8 * c) * 33 + n;
;         v4u o; o.x = pk2(s[0 * 33], s[1 * 33]); o.y = pk2(s[2 * 33], s[3 * 33]); o.z = pk2(s[4 * 33], s[5 * 33]); o.w = pk2(s[6 * 33], s[7 * 33]);
;         *(GAS v4u*)(WT + (size_t)(dst_row0 + n) * ldk + dst_k0 + k0 + 8 * c) = o; }
;     LDS_WAIT(); asm volatile("" ::: "memory");
; __global__ void __launch_bounds__(NWAVES * 64, 2) fwd(Args args) {
;     ...
;                 if (blockIdx.x < 64) for (int it = ((int)blockIdx.x - 32) * NWAVES + wave; it < I_BA + I_BB + I_O + I_UP + I_DN; it += 32 * NWAVES) {
;                     int r = it;
;                     if (r < I_BA) { const int kb = r / 32, nb = r % 32; p0_transpose_item(wba, 1024, 32 * nb, 64 * kb, WBAB_T, 1024, 32 * nb, 0, scr, lane); continue; } r -= I_BA;
;                     if (r < I_BB) { const int kb = r / 32, nb = r % 32; p0_transpose_item(wbb, 1024, 32 * nb, 64 * kb, WBAB_T, 1024, 32 * nb, 512, scr, lane); continue; } r -= I_BB;
;                     if (r < I_O) { const int kb = r / 32, nb = r % 32; p0_transpose_item(wo, 1024, 32 * nb, 64 * kb, WO_T, 1024, 32 * nb, 0, scr, lane); continue; } r -= I_O;
;                     if (r < I_UP) { const int kb = r / 128, nb = r % 128; p0_transpose_item(wup, FF, 32 * nb, 64 * kb, WUP_T, 1024, 32 * nb, 0, scr, lane); continue; } r -= I_UP;
;                     { const int kb = r / 32, nb = r % 32; p0_transpose_item(wdn, 1024, 32 * nb, 64 * kb, WDN_T, FF, 32 * nb, 0, scr, lane); }
	v_cvt_pk_bf16_f32 v88, v64, v66
	v_cvt_pk_bf16_f32 v89, v68, v70
	v_cvt_pk_bf16_f32 v90, v72, v74
	v_cvt_pk_bf16_f32 v91, v76, v78
	v_cvt_pk_bf16_f32 v92, v65, v67
	v_cvt_pk_bf16_f32 v93, v69, v71
	v_cvt_pk_bf16_f32 v94, v73, v75
	v_cvt_pk_bf16_f32 v95, v77, v79
	global_store_dwordx4 v116, v[80:83], s[86:87] offset:1024
	global_store_dwordx4 v117, v[84:87], s[86:87] offset:1024
	global_store_dwordx4 v118, v[88:91], s[86:87] offset:1024
	global_store_dwordx4 v119, v[92:95], s[86:87] offset:1024
	s_add_u32 s46, s46, 0x200000
	s_addc_u32 s47, s47, 0
	global_load_dwordx4 v[192:195], v108, s[46:47] nt
	global_load_dwordx4 v[196:199], v109, s[46:47] nt
	global_load_dwordx4 v[200:203], v110, s[46:47] nt
	global_load_dwordx4 v[204:207], v111, s[46:47] nt
	global_load_dwordx4 v[208:211], v112, s[46:47] nt
	global_load_dwordx4 v[212:215], v113, s[46:47] nt
	global_load_dwordx4 v[216:219], v114, s[46:47] nt
	global_load_dwordx4 v[220:223], v115, s[46:47] nt
	s_waitcnt vmcnt(16)
	ds_write2_b32 v32, v128, v129 offset1:1
	ds_write2_b32 v32, v130, v131 offset0:2 offset1:3
	ds_write2_b32 v33, v132, v133 offset1:1
	ds_write2_b32 v34, v134, v135 offset1:1
	ds_write2_b32 v35, v136, v137 offset1:1
	ds_write2_b32 v36, v138, v139 offset1:1
	ds_write2_b32 v37, v140, v141 offset1:1
	ds_write2_b32 v38, v142, v143 offset1:1
	ds_write2_b32 v39, v144, v145 offset1:1
	ds_write2_b32 v40, v146, v147 offset1:1
	ds_write2_b32 v41, v148, v149 offset1:1
	ds_write2_b32 v42, v150, v151 offset1:1
	ds_write2_b32 v43, v152, v153 offset1:1
	ds_write2_b32 v44, v154, v155 offset1:1
	ds_write2_b32 v45, v156, v157 offset1:1
	ds_write2_b32 v46, v158, v159 offset1:1
	s_waitcnt lgkmcnt(0)
	ds_read2_b32 v[48:49], v31 offset0:0 offset1:8
	ds_read2_b32 v[50:51], v31 offset0:33 offset1:41
	ds_read2_b32 v[52:53], v31 offset0:66 offset1:74
	ds_read2_b32 v[54:55], v31 offset0:99 offset1:107
	ds_read2_b32 v[56:57], v31 offset0:132 offset1:140
	ds_read2_b32 v[58:59], v31 offset0:165 offset1:173
	ds_read2_b32 v[60:61], v31 offset0:198 offset1:206
	ds_read2_b32 v[62:63], v31 offset0:231 offset1:239
	ds_read2_b32 v[64:65], v31 offset0:16 offset1:24
	ds_read2_b32 v[66:67], v31 offset0:49 offset1:57
	ds_read2_b32 v[68:69], v31 offset0:82 offset1:90
	ds_read2_b32 v[70:71], v31 offset0:115 offset1:123
	ds_read2_b32 v[72:73], v31 offset0:148 offset1:156
	ds_read2_b32 v[74:75], v31 offset0:181 offset1:189
	ds_read2_b32 v[76:77], v31 offset0:214 offset1:222
	ds_read2_b32 v[78:79], v31 offset0:247 offset1:255
	s_waitcnt lgkmcnt(8)
	v_cvt_pk_bf16_f32 v80, v48, v50
	v_cvt_pk_bf16_f32 v81, v52, v54
	v_cvt_pk_bf16_f32 v82, v56, v58
	v_cvt_pk_bf16_f32 v83, v60, v62
	v_cvt_pk_bf16_f32 v84, v49, v51
	v_cvt_pk_bf16_f32 v85, v53, v55
	v_cvt_pk_bf16_f32 v86, v57, v59
	v_cvt_pk_bf16_f32 v87, v61, v63
	s_waitcnt lgkmcnt(0)
	v_cvt_pk_bf16_f32 v88, v64, v66
	v_cvt_pk_bf16_f32 v89, v68, v70
	v_cvt_pk_bf16_f32 v90, v72, v74
	v_cvt_pk_bf16_f32 v91, v76, v78
	v_cvt_pk_bf16_f32 v92, v65, v67
	v_cvt_pk_bf16_f32 v93, v69, v71
	v_cvt_pk_bf16_f32 v94, v73, v75
	v_cvt_pk_bf16_f32 v95, v77, v79
	global_store_dwordx4 v116, v[80:83], s[86:87] offset:1280
	global_store_dwordx4 v117, v[84:87], s[86:87] offset:1280
	global_store_dwordx4 v118, v[88:91], s[86:87] offset:1280
	global_store_dwordx4 v119, v[92:95], s[86:87] offset:1280
	global_load_dwordx4 v[128:131], v100, s[50:51] nt
	global_load_dwordx4 v[132:135], v101, s[50:51] nt
	global_load_dwordx4 v[136:139], v102, s[50:51] nt
	global_load_dwordx4 v[140:143], v103, s[50:51] nt
	global_load_dwordx4 v[144:147], v104, s[50:51] nt
	global_load_dwordx4 v[148:151], v105, s[50:51] nt
	global_load_dwordx4 v[152:155], v106, s[50:51] nt
	global_load_dwordx4 v[156:159], v107, s[50:51] nt
	s_waitcnt vmcnt(16)
	ds_write2_b32 v32, v160, v161 offset1:1
	ds_write2_b32 v32, v162, v163 offset0:2 offset1:3
	ds_write2_b32 v33, v164, v165 offset1:1
	ds_write2_b32 v34, v166, v167 offset1:1
	ds_write2_b32 v35, v168, v169 offset1:1
	ds_write2_b32 v36, v170, v171 offset1:1
	ds_write2_b32 v37, v172, v173 offset1:1
	ds_write2_b32 v38, v174, v175 offset1:1
	ds_write2_b32 v39, v176, v177 offset1:1
	ds_write2_b32 v40, v178, v179 offset1:1
	ds_write2_b32 v41, v180, v181 offset1:1
	ds_write2_b32 v42, v182, v183 offset1:1
	ds_write2_b32 v43, v184, v185 offset1:1
	ds_write2_b32 v44, v186, v187 offset1:1
	ds_write2_b32 v45, v188, v189 offset1:1
	ds_write2_b32 v46, v190, v191 offset1:1
	s_waitcnt lgkmcnt(0)
	ds_read2_b32 v[48:49], v31 offset0:0 offset1:8
	ds_read2_b32 v[50:51], v31 offset0:33 offset1:41
	ds_read2_b32 v[52:53], v31 offset0:66 offset1:74
	ds_read2_b32 v[54:55], v31 offset0:99 offset1:107
	ds_read2_b32 v[56:57], v31 offset0:132 offset1:140
	ds_read2_b32 v[58:59], v31 offset0:165 offset1:173
	ds_read2_b32 v[60:61], v31 offset0:198 offset1:206
	ds_read2_b32 v[62:63], v31 offset0:231 offset1:239
	ds_read2_b32 v[64:65], v31 offset0:16 offset1:24
	ds_read2_b32 v[66:67], v31 offset0:49 offset1:57
	ds_read2_b32 v[68:69], v31 offset0:82 offset1:90
	ds_read2_b32 v[70:71], v31 offset0:115 offset1:123
	ds_read2_b32 v[72:73], v31 offset0:148 offset1:156
	ds_read2_b32 v[74:75], v31 offset0:181 offset1:189
	ds_read2_b32 v[76:77], v31 offset0:214 offset1:222
	ds_read2_b32 v[78:79], v31 offset0:247 offset1:255
	s_waitcnt lgkmcnt(8)
	v_cvt_pk_bf16_f32 v80, v48, v50
	v_cvt_pk_bf16_f32 v81, v52, v54
	v_cvt_pk_bf16_f32 v82, v56, v58
	v_cvt_pk_bf16_f32 v83, v60, v62
	v_cvt_pk_bf16_f32 v84, v49, v51
	v_cvt_pk_bf16_f32 v85, v53, v55
	v_cvt_pk_bf16_f32 v86, v57, v59
	v_cvt_pk_bf16_f32 v87, v61, v63
	s_waitcnt lgkmcnt(0)
; #define GAS __attribute__((address_space(1)))
; #define LAS __attribute__((address_space(3)))
; #define LDS_WAIT() asm volatile("s_waitcnt lgkmcnt(0)" ::: "memory")
; __device__ __forceinline__ void p0_transpose_item(const float* W, int ldw, int src_col0, int k0, bf16_t* WT, int ldk, int dst_row0, int dst_k0, LAS float* scr, int lane) {
; #pragma unroll
;     for (int i = 0; i < 8; ++i) { const int kk = 8 * i + (lane >> 3), n4 = 4 * (lane & 7);
;         const f32x4 w = *(const GAS f32x4*)(W + (size_t)(k0 + kk) * ldw + src_col0 + n4); LAS float* d = scr + kk * 33 + n4; d[0] = w[0]; d[1] = w[1]; d[2] = w[2]; d[3] = w[3]; }
;     LDS_WAIT(); asm volatile("" ::: "memory");
;     const int c = lane & 7;
; #pragma unroll
;     for (int j = 0; j < 4; ++j) { const int n = (lane >> 3) + 8 * j; const LAS float* s = scr + (8 * c) * 33 + n;
;         v4u o; o.x = pk2(s[0 * 33], s[1 * 33]); o.y = pk2(s[2 * 33], s[3 * 33]); o.z = pk2(s[4 * 33], s[5 * 33]); o.w = pk2(s[6 * 33], s[7 * 33]);
;         *(GAS v4u*)(WT + (size_t)(dst_row0 + n) * ldk + dst_k0 + k0 + 8 * c) = o; }
;     LDS_WAIT(); asm volatile("" ::: "memory");
; __global__ void __launch_bounds__(NWAVES * 64, 2) fwd(Args args) {
;     ...
;                 if (blockIdx.x < 64) for (int it = ((int)blockIdx.x - 32) * NWAVES + wave; it < I_BA + I_BB + I_O + I_UP + I_DN; it += 32 * NWAVES) {
;                     int r = it;
;                     if (r < I_BA) { const int kb = r / 32, nb = r % 32; p0_transpose_item(wba, 1024, 32 * nb, 64 * kb, WBAB_T, 1024, 32 * nb, 0, scr, lane); continue; } r -= I_BA;
;                     if (r < I_BB) { const int kb = r / 32, nb = r % 32; p0_transpose_item(wbb, 1024, 32 * nb, 64 * kb, WBAB_T, 1024, 32 * nb, 512, scr, lane); continue; } r -= I_BB;
;                     if (r < I_O) { const int kb = r / 32, nb = r % 32; p0_transpose_item(wo, 1024, 32 * nb, 64 * kb, WO_T, 1024, 32 * nb, 0, scr, lane); continue; } r -= I_O;
;                     if (r < I_UP) { const int kb = r / 128, nb = r % 128; p0_transpose_item(wup, FF, 32 * nb, 64 * kb, WUP_T, 1024, 32 * nb, 0, scr, lane); continue; } r -= I_UP;
;                     { const int kb = r / 32, nb = r % 32; p0_transpose_item(wdn, 1024, 32 * nb, 64 * kb, WDN_T, FF, 32 * nb, 0, scr, lane); }
	v_cvt_pk_bf16_f32 v88, v64, v66
	v_cvt_pk_bf16_f32 v89, v68, v70
	v_cvt_pk_bf16_f32 v90, v72, v74
	v_cvt_pk_bf16_f32 v91, v76, v78
	v_cvt_pk_bf16_f32 v92, v65, v67
	v_cvt_pk_bf16_f32 v93, v69, v71
	v_cvt_pk_bf16_f32 v94, v73, v75
	v_cvt_pk_bf16_f32 v95, v77, v79
	global_store_dwordx4 v116, v[80:83], s[86:87] offset:1536
	global_store_dwordx4 v117, v[84:87], s[86:87] offset:1536
	global_store_dwordx4 v118, v[88:91], s[86:87] offset:1536
	global_store_dwordx4 v119, v[92:95], s[86:87] offset:1536
	s_add_u32 s50, s50, 0x200000
	s_addc_u32 s51, s51, 0
	global_load_dwordx4 v[160:163], v100, s[50:51] nt
	global_load_dwordx4 v[164:167], v101, s[50:51] nt
	global_load_dwordx4 v[168:171], v102, s[50:51] nt
	global_load_dwordx4 v[172:175], v103, s[50:51] nt
	global_load_dwordx4 v[176:179], v104, s[50:51] nt
	global_load_dwordx4 v[180:183], v105, s[50:51] nt
	global_load_dwordx4 v[184:187], v106, s[50:51] nt
	global_load_dwordx4 v[188:191], v107, s[50:51] nt
	s_waitcnt vmcnt(16)
	ds_write2_b32 v32, v192, v193 offset1:1
	ds_write2_b32 v32, v194, v195 offset0:2 offset1:3
	ds_write2_b32 v33, v196, v197 offset1:1
	ds_write2_b32 v34, v198, v199 offset1:1
	ds_write2_b32 v35, v200, v201 offset1:1
	ds_write2_b32 v36, v202, v203 offset1:1
	ds_write2_b32 v37, v204, v205 offset1:1
	ds_write2_b32 v38, v206, v207 offset1:1
	ds_write2_b32 v39, v208, v209 offset1:1
	ds_write2_b32 v40, v210, v211 offset1:1
	ds_write2_b32 v41, v212, v213 offset1:1
	ds_write2_b32 v42, v214, v215 offset1:1
	ds_write2_b32 v43, v216, v217 offset1:1
	ds_write2_b32 v44, v218, v219 offset1:1
	ds_write2_b32 v45, v220, v221 offset1:1
	ds_write2_b32 v46, v222, v223 offset1:1
	s_waitcnt lgkmcnt(0)
	ds_read2_b32 v[48:49], v31 offset0:0 offset1:8
	ds_read2_b32 v[50:51], v31 offset0:33 offset1:41
	ds_read2_b32 v[52:53], v31 offset0:66 offset1:74
	ds_read2_b32 v[54:55], v31 offset0:99 offset1:107
	ds_read2_b32 v[56:57], v31 offset0:132 offset1:140
	ds_read2_b32 v[58:59], v31 offset0:165 offset1:173
	ds_read2_b32 v[60:61], v31 offset0:198 offset1:206
	ds_read2_b32 v[62:63], v31 offset0:231 offset1:239
	ds_read2_b32 v[64:65], v31 offset0:16 offset1:24
	ds_read2_b32 v[66:67], v31 offset0:49 offset1:57
	ds_read2_b32 v[68:69], v31 offset0:82 offset1:90
	ds_read2_b32 v[70:71], v31 offset0:115 offset1:123
	ds_read2_b32 v[72:73], v31 offset0:148 offset1:156
	ds_read2_b32 v[74:75], v31 offset0:181 offset1:189
	ds_read2_b32 v[76:77], v31 offset0:214 offset1:222
	ds_read2_b32 v[78:79], v31 offset0:247 offset1:255
	s_waitcnt lgkmcnt(8)
	v_cvt_pk_bf16_f32 v80, v48, v50
	v_cvt_pk_bf16_f32 v81, v52, v54
	v_cvt_pk_bf16_f32 v82, v56, v58
	v_cvt_pk_bf16_f32 v83, v60, v62
	v_cvt_pk_bf16_f32 v84, v49, v51
	v_cvt_pk_bf16_f32 v85, v53, v55
	v_cvt_pk_bf16_f32 v86, v57, v59
	v_cvt_pk_bf16_f32 v87, v61, v63
	s_waitcnt lgkmcnt(0)
	v_cvt_pk_bf16_f32 v88, v64, v66
	v_cvt_pk_bf16_f32 v89, v68, v70
	v_cvt_pk_bf16_f32 v90, v72, v74
	v_cvt_pk_bf16_f32 v91, v76, v78
	v_cvt_pk_bf16_f32 v92, v65, v67
	v_cvt_pk_bf16_f32 v93, v69, v71
	v_cvt_pk_bf16_f32 v94, v73, v75
	v_cvt_pk_bf16_f32 v95, v77, v79
	global_store_dwordx4 v116, v[80:83], s[86:87] offset:1792
	global_store_dwordx4 v117, v[84:87], s[86:87] offset:1792
	global_store_dwordx4 v118, v[88:91], s[86:87] offset:1792
	global_store_dwordx4 v119, v[92:95], s[86:87] offset:1792
	s_add_u32 s50, s50, 0x200000
	s_addc_u32 s51, s51, 0
	global_load_dwordx4 v[192:195], v100, s[50:51] nt
	global_load_dwordx4 v[196:199], v101, s[50:51] nt
	global_load_dwordx4 v[200:203], v102, s[50:51] nt
	global_load_dwordx4 v[204:207], v103, s[50:51] nt
	global_load_dwordx4 v[208:211], v104, s[50:51] nt
	global_load_dwordx4 v[212:215], v105, s[50:51] nt
	global_load_dwordx4 v[216:219], v106, s[50:51] nt
	global_load_dwordx4 v[220:223], v107, s[50:51] nt
	s_waitcnt vmcnt(16)
	ds_write2_b32 v32, v128, v129 offset1:1
	ds_write2_b32 v32, v130, v131 offset0:2 offset1:3
	ds_write2_b32 v33, v132, v133 offset1:1
	ds_write2_b32 v34, v134, v135 offset1:1
	ds_write2_b32 v35, v136, v137 offset1:1
	ds_write2_b32 v36, v138, v139 offset1:1
	ds_write2_b32 v37, v140, v141 offset1:1
	ds_write2_b32 v38, v142, v143 offset1:1
	ds_write2_b32 v39, v144, v145 offset1:1
	ds_write2_b32 v40, v146, v147 offset1:1
	ds_write2_b32 v41, v148, v149 offset1:1
	ds_write2_b32 v42, v150, v151 offset1:1
	ds_write2_b32 v43, v152, v153 offset1:1
	ds_write2_b32 v44, v154, v155 offset1:1
	ds_write2_b32 v45, v156, v157 offset1:1
	ds_write2_b32 v46, v158, v159 offset1:1
	s_waitcnt lgkmcnt(0)
	ds_read2_b32 v[48:49], v31 offset0:0 offset1:8
	ds_read2_b32 v[50:51], v31 offset0:33 offset1:41
	ds_read2_b32 v[52:53], v31 offset0:66 offset1:74
	ds_read2_b32 v[54:55], v31 offset0:99 offset1:107
	ds_read2_b32 v[56:57], v31 offset0:132 offset1:140
	ds_read2_b32 v[58:59], v31 offset0:165 offset1:173
	ds_read2_b32 v[60:61], v31 offset0:198 offset1:206
	ds_read2_b32 v[62:63], v31 offset0:231 offset1:239
	ds_read2_b32 v[64:65], v31 offset0:16 offset1:24
	ds_read2_b32 v[66:67], v31 offset0:49 offset1:57
	ds_read2_b32 v[68:69], v31 offset0:82 offset1:90
	ds_read2_b32 v[70:71], v31 offset0:115 offset1:123
	ds_read2_b32 v[72:73], v31 offset0:148 offset1:156
	ds_read2_b32 v[74:75], v31 offset0:181 offset1:189
	ds_read2_b32 v[76:77], v31 offset0:214 offset1:222
	ds_read2_b32 v[78:79], v31 offset0:247 offset1:255
	s_waitcnt lgkmcnt(8)
	v_cvt_pk_bf16_f32 v80, v48, v50
	v_cvt_pk_bf16_f32 v81, v52, v54
	v_cvt_pk_bf16_f32 v82, v56, v58
	v_cvt_pk_bf16_f32 v83, v60, v62
	v_cvt_pk_bf16_f32 v84, v49, v51
	v_cvt_pk_bf16_f32 v85, v53, v55
	v_cvt_pk_bf16_f32 v86, v57, v59
	v_cvt_pk_bf16_f32 v87, v61, v63
	s_waitcnt lgkmcnt(0)
; #define GAS __attribute__((address_space(1)))
; #define LAS __attribute__((address_space(3)))
; #define LDS_WAIT() asm volatile("s_waitcnt lgkmcnt(0)" ::: "memory")
; __device__ __forceinline__ void p0_transpose_item(const float* W, int ldw, int src_col0, int k0, bf16_t* WT, int ldk, int dst_row0, int dst_k0, LAS float* scr, int lane) {
; #pragma unroll
;     for (int i = 0; i < 8; ++i) { const int kk = 8 * i + (lane >> 3), n4 = 4 * (lane & 7);
;         const f32x4 w = *(const GAS f32x4*)(W + (size_t)(k0 + kk) * ldw + src_col0 + n4); LAS float* d = scr + kk * 33 + n4; d[0] = w[0]; d[1] = w[1]; d[2] = w[2]; d[3] = w[3]; }
;     LDS_WAIT(); asm volatile("" ::: "memory");
;     const int c = lane & 7;
; #pragma unroll
;     for (int j = 0; j < 4; ++j) { const int n = (lane >> 3) + 8 * j; const LAS float* s = scr + (8 * c) * 33 + n;
;         v4u o; o.x = pk2(s[0 * 33], s[1 * 33]); o.y = pk2(s[2 * 33], s[3 * 33]); o.z = pk2(s[4 * 33], s[5 * 33]); o.w = pk2(s[6 * 33], s[7 * 33]);
;         *(GAS v4u*)(WT + (size_t)(dst_row0 + n) * ldk + dst_k0 + k0 + 8 * c) = o; }
;     LDS_WAIT(); asm volatile("" ::: "memory");
; __global__ void __launch_bounds__(NWAVES * 64, 2) fwd(Args args) {
;     ...
;                 if (blockIdx.x < 64) for (int it = ((int)blockIdx.x - 32) * NWAVES + wave; it < I_BA + I_BB + I_O + I_UP + I_DN; it += 32 * NWAVES) {
;                     int r = it;
;                     if (r < I_BA) { const int kb = r / 32, nb = r % 32; p0_transpose_item(wba, 1024, 32 * nb, 64 * kb, WBAB_T, 1024, 32 * nb, 0, scr, lane); continue; } r -= I_BA;
;                     if (r < I_BB) { const int kb = r / 32, nb = r % 32; p0_transpose_item(wbb, 1024, 32 * nb, 64 * kb, WBAB_T, 1024, 32 * nb, 512, scr, lane); continue; } r -= I_BB;
;                     if (r < I_O) { const int kb = r / 32, nb = r % 32; p0_transpose_item(wo, 1024, 32 * nb, 64 * kb, WO_T, 1024, 32 * nb, 0, scr, lane); continue; } r -= I_O;
;                     if (r < I_UP) { const int kb = r / 128, nb = r % 128; p0_transpose_item(wup, FF, 32 * nb, 64 * kb, WUP_T, 1024, 32 * nb, 0, scr, lane); continue; } r -= I_UP;
;                     { const int kb = r / 32, nb = r % 32; p0_transpose_item(wdn, 1024, 32 * nb, 64 * kb, WDN_T, FF, 32 * nb, 0, scr, lane); }
	v_cvt_pk_bf16_f32 v88, v64, v66
	v_cvt_pk_bf16_f32 v89, v68, v70
	v_cvt_pk_bf16_f32 v90, v72, v74
	v_cvt_pk_bf16_f32 v91, v76, v78
	v_cvt_pk_bf16_f32 v92, v65, v67
	v_cvt_pk_bf16_f32 v93, v69, v71
	v_cvt_pk_bf16_f32 v94, v73, v75
	v_cvt_pk_bf16_f32 v95, v77, v79
	global_store_dwordx4 v120, v[80:83], s[88:89]
	global_store_dwordx4 v121, v[84:87], s[88:89]
	global_store_dwordx4 v122, v[88:91], s[88:89]
	global_store_dwordx4 v123, v[92:95], s[88:89]
	s_add_u32 s50, s50, 0x200000
	s_addc_u32 s51, s51, 0
	global_load_dwordx4 v[128:131], v100, s[50:51] nt
	global_load_dwordx4 v[132:135], v101, s[50:51] nt
	global_load_dwordx4 v[136:139], v102, s[50:51] nt
	global_load_dwordx4 v[140:143], v103, s[50:51] nt
	global_load_dwordx4 v[144:147], v104, s[50:51] nt
	global_load_dwordx4 v[148:151], v105, s[50:51] nt
	global_load_dwordx4 v[152:155], v106, s[50:51] nt
	global_load_dwordx4 v[156:159], v107, s[50:51] nt
	s_waitcnt vmcnt(16)
	ds_write2_b32 v32, v160, v161 offset1:1
	ds_write2_b32 v32, v162, v163 offset0:2 offset1:3
	ds_write2_b32 v33, v164, v165 offset1:1
	ds_write2_b32 v34, v166, v167 offset1:1
	ds_write2_b32 v35, v168, v169 offset1:1
	ds_write2_b32 v36, v170, v171 offset1:1
	ds_write2_b32 v37, v172, v173 offset1:1
	ds_write2_b32 v38, v174, v175 offset1:1
	ds_write2_b32 v39, v176, v177 offset1:1
	ds_write2_b32 v40, v178, v179 offset1:1
	ds_write2_b32 v41, v180, v181 offset1:1
	ds_write2_b32 v42, v182, v183 offset1:1
	ds_write2_b32 v43, v184, v185 offset1:1
	ds_write2_b32 v44, v186, v187 offset1:1
	ds_write2_b32 v45, v188, v189 offset1:1
	ds_write2_b32 v46, v190, v191 offset1:1
	s_waitcnt lgkmcnt(0)
	ds_read2_b32 v[48:49], v31 offset0:0 offset1:8
	ds_read2_b32 v[50:51], v31 offset0:33 offset1:41
	ds_read2_b32 v[52:53], v31 offset0:66 offset1:74
	ds_read2_b32 v[54:55], v31 offset0:99 offset1:107
	ds_read2_b32 v[56:57], v31 offset0:132 offset1:140
	ds_read2_b32 v[58:59], v31 offset0:165 offset1:173
	ds_read2_b32 v[60:61], v31 offset0:198 offset1:206
	ds_read2_b32 v[62:63], v31 offset0:231 offset1:239
	ds_read2_b32 v[64:65], v31 offset0:16 offset1:24
	ds_read2_b32 v[66:67], v31 offset0:49 offset1:57
	ds_read2_b32 v[68:69], v31 offset0:82 offset1:90
	ds_read2_b32 v[70:71], v31 offset0:115 offset1:123
	ds_read2_b32 v[72:73], v31 offset0:148 offset1:156
	ds_read2_b32 v[74:75], v31 offset0:181 offset1:189
	ds_read2_b32 v[76:77], v31 offset0:214 offset1:222
	ds_read2_b32 v[78:79], v31 offset0:247 offset1:255
	s_waitcnt lgkmcnt(8)
	v_cvt_pk_bf16_f32 v80, v48, v50
	v_cvt_pk_bf16_f32 v81, v52, v54
	v_cvt_pk_bf16_f32 v82, v56, v58
	v_cvt_pk_bf16_f32 v83, v60, v62
	v_cvt_pk_bf16_f32 v84, v49, v51
	v_cvt_pk_bf16_f32 v85, v53, v55
	v_cvt_pk_bf16_f32 v86, v57, v59
	v_cvt_pk_bf16_f32 v87, v61, v63
	s_waitcnt lgkmcnt(0)
	v_cvt_pk_bf16_f32 v88, v64, v66
	v_cvt_pk_bf16_f32 v89, v68, v70
	v_cvt_pk_bf16_f32 v90, v72, v74
	v_cvt_pk_bf16_f32 v91, v76, v78
	v_cvt_pk_bf16_f32 v92, v65, v67
	v_cvt_pk_bf16_f32 v93, v69, v71
	v_cvt_pk_bf16_f32 v94, v73, v75
	v_cvt_pk_bf16_f32 v95, v77, v79
	global_store_dwordx4 v120, v[80:83], s[88:89] offset:1024
	global_store_dwordx4 v121, v[84:87], s[88:89] offset:1024
	global_store_dwordx4 v122, v[88:91], s[88:89] offset:1024
	global_store_dwordx4 v123, v[92:95], s[88:89] offset:1024
	s_add_u32 s50, s50, 0x200000
	s_addc_u32 s51, s51, 0
	global_load_dwordx4 v[160:163], v100, s[50:51] nt
	global_load_dwordx4 v[164:167], v101, s[50:51] nt
	global_load_dwordx4 v[168:171], v102, s[50:51] nt
	global_load_dwordx4 v[172:175], v103, s[50:51] nt
	global_load_dwordx4 v[176:179], v104, s[50:51] nt
	global_load_dwordx4 v[180:183], v105, s[50:51] nt
	global_load_dwordx4 v[184:187], v106, s[50:51] nt
	global_load_dwordx4 v[188:191], v107, s[50:51] nt
	s_waitcnt vmcnt(16)
	ds_write2_b32 v32, v192, v193 offset1:1
	ds_write2_b32 v32, v194, v195 offset0:2 offset1:3
	ds_write2_b32 v33, v196, v197 offset1:1
	ds_write2_b32 v34, v198, v199 offset1:1
	ds_write2_b32 v35, v200, v201 offset1:1
	ds_write2_b32 v36, v202, v203 offset1:1
	ds_write2_b32 v37, v204, v205 offset1:1
	ds_write2_b32 v38, v206, v207 offset1:1
	ds_write2_b32 v39, v208, v209 offset1:1
	ds_write2_b32 v40, v210, v211 offset1:1
	ds_write2_b32 v41, v212, v213 offset1:1
	ds_write2_b32 v42, v214, v215 offset1:1
	ds_write2_b32 v43, v216, v217 offset1:1
	ds_write2_b32 v44, v218, v219 offset1:1
	ds_write2_b32 v45, v220, v221 offset1:1
	ds_write2_b32 v46, v222, v223 offset1:1
	s_waitcnt lgkmcnt(0)
	ds_read2_b32 v[48:49], v31 offset0:0 offset1:8
	ds_read2_b32 v[50:51], v31 offset0:33 offset1:41
	ds_read2_b32 v[52:53], v31 offset0:66 offset1:74
	ds_read2_b32 v[54:55], v31 offset0:99 offset1:107
	ds_read2_b32 v[56:57], v31 offset0:132 offset1:140
	ds_read2_b32 v[58:59], v31 offset0:165 offset1:173
	ds_read2_b32 v[60:61], v31 offset0:198 offset1:206
	ds_read2_b32 v[62:63], v31 offset0:231 offset1:239
	ds_read2_b32 v[64:65], v31 offset0:16 offset1:24
	ds_read2_b32 v[66:67], v31 offset0:49 offset1:57
	ds_read2_b32 v[68:69], v31 offset0:82 offset1:90
	ds_read2_b32 v[70:71], v31 offset0:115 offset1:123
	ds_read2_b32 v[72:73], v31 offset0:148 offset1:156
	ds_read2_b32 v[74:75], v31 offset0:181 offset1:189
	ds_read2_b32 v[76:77], v31 offset0:214 offset1:222
	ds_read2_b32 v[78:79], v31 offset0:247 offset1:255
	s_waitcnt lgkmcnt(8)
	v_cvt_pk_bf16_f32 v80, v48, v50
	v_cvt_pk_bf16_f32 v81, v52, v54
	v_cvt_pk_bf16_f32 v82, v56, v58
	v_cvt_pk_bf16_f32 v83, v60, v62
	v_cvt_pk_bf16_f32 v84, v49, v51
	v_cvt_pk_bf16_f32 v85, v53, v55
	v_cvt_pk_bf16_f32 v86, v57, v59
	v_cvt_pk_bf16_f32 v87, v61, v63
	s_waitcnt lgkmcnt(0)
; #define GAS __attribute__((address_space(1)))
; #define LAS __attribute__((address_space(3)))
; #define LDS_WAIT() asm volatile("s_waitcnt lgkmcnt(0)" ::: "memory")
; __device__ __forceinline__ void p0_transpose_item(const float* W, int ldw, int src_col0, int k0, bf16_t* WT, int ldk, int dst_row0, int dst_k0, LAS float* scr, int lane) {
; #pragma unroll
;     for (int i = 0; i < 8; ++i) { const int kk = 8 * i + (lane >> 3), n4 = 4 * (lane & 7);
;         const f32x4 w = *(const GAS f32x4*)(W + (size_t)(k0 + kk) * ldw + src_col0 + n4); LAS float* d = scr + kk * 33 + n4; d[0] = w[0]; d[1] = w[1]; d[2] = w[2]; d[3] = w[3]; }
;     LDS_WAIT(); asm volatile("" ::: "memory");
;     const int c = lane & 7;
; #pragma unroll
;     for (int j = 0; j < 4; ++j) { const int n = (lane >> 3) + 8 * j; const LAS float* s = scr + (8 * c) * 33 + n;
;         v4u o; o.x = pk2(s[0 * 33], s[1 * 33]); o.y = pk2(s[2 * 33], s[3 * 33]); o.z = pk2(s[4 * 33], s[5 * 33]); o.w = pk2(s[6 * 33], s[7 * 33]);
;         *(GAS v4u*)(WT + (size_t)(dst_row0 + n) * ldk + dst_k0 + k0 + 8 * c) = o; }
;     LDS_WAIT(); asm volatile("" ::: "memory");
; __global__ void __launch_bounds__(NWAVES * 64, 2) fwd(Args args) {
;     ...
;                 if (blockIdx.x < 64) for (int it = ((int)blockIdx.x - 32) * NWAVES + wave; it < I_BA + I_BB + I_O + I_UP + I_DN; it += 32 * NWAVES) {
;                     int r = it;
;                     if (r < I_BA) { const int kb = r / 32, nb = r % 32; p0_transpose_item(wba, 1024, 32 * nb, 64 * kb, WBAB_T, 1024, 32 * nb, 0, scr, lane); continue; } r -= I_BA;
;                     if (r < I_BB) { const int kb = r / 32, nb = r % 32; p0_transpose_item(wbb, 1024, 32 * nb, 64 * kb, WBAB_T, 1024, 32 * nb, 512, scr, lane); continue; } r -= I_BB;
;                     if (r < I_O) { const int kb = r / 32, nb = r % 32; p0_transpose_item(wo, 1024, 32 * nb, 64 * kb, WO_T, 1024, 32 * nb, 0, scr, lane); continue; } r -= I_O;
;                     if (r < I_UP) { const int kb = r / 128, nb = r % 128; p0_transpose_item(wup, FF, 32 * nb, 64 * kb, WUP_T, 1024, 32 * nb, 0, scr, lane); continue; } r -= I_UP;
;                     { const int kb = r / 32, nb = r % 32; p0_transpose_item(wdn, 1024, 32 * nb, 64 * kb, WDN_T, FF, 32 * nb, 0, scr, lane); }
	v_cvt_pk_bf16_f32 v88, v64, v66
	v_cvt_pk_bf16_f32 v89, v68, v70
	v_cvt_pk_bf16_f32 v90, v72, v74
	v_cvt_pk_bf16_f32 v91, v76, v78
	v_cvt_pk_bf16_f32 v92, v65, v67
	v_cvt_pk_bf16_f32 v93, v69, v71
	v_cvt_pk_bf16_f32 v94, v73, v75
	v_cvt_pk_bf16_f32 v95, v77, v79
	global_store_dwordx4 v120, v[80:83], s[88:89] offset:2048
	global_store_dwordx4 v121, v[84:87], s[88:89] offset:2048
	global_store_dwordx4 v122, v[88:91], s[88:89] offset:2048
	global_store_dwordx4 v123, v[92:95], s[88:89] offset:2048
	s_add_u32 s50, s50, 0x200000
	s_addc_u32 s51, s51, 0
	global_load_dwordx4 v[192:195], v100, s[50:51] nt
	global_load_dwordx4 v[196:199], v101, s[50:51] nt
	global_load_dwordx4 v[200:203], v102, s[50:51] nt
	global_load_dwordx4 v[204:207], v103, s[50:51] nt
	global_load_dwordx4 v[208:211], v104, s[50:51] nt
	global_load_dwordx4 v[212:215], v105, s[50:51] nt
	global_load_dwordx4 v[216:219], v106, s[50:51] nt
	global_load_dwordx4 v[220:223], v107, s[50:51] nt
	s_waitcnt vmcnt(16)
	ds_write2_b32 v32, v128, v129 offset1:1
	ds_write2_b32 v32, v130, v131 offset0:2 offset1:3
	ds_write2_b32 v33, v132, v133 offset1:1
	ds_write2_b32 v34, v134, v135 offset1:1
	ds_write2_b32 v35, v136, v137 offset1:1
	ds_write2_b32 v36, v138, v139 offset1:1
	ds_write2_b32 v37, v140, v141 offset1:1
	ds_write2_b32 v38, v142, v143 offset1:1
	ds_write2_b32 v39, v144, v145 offset1:1
	ds_write2_b32 v40, v146, v147 offset1:1
	ds_write2_b32 v41, v148, v149 offset1:1
	ds_write2_b32 v42, v150, v151 offset1:1
	ds_write2_b32 v43, v152, v153 offset1:1
	ds_write2_b32 v44, v154, v155 offset1:1
	ds_write2_b32 v45, v156, v157 offset1:1
	ds_write2_b32 v46, v158, v159 offset1:1
	s_waitcnt lgkmcnt(0)
	ds_read2_b32 v[48:49], v31 offset0:0 offset1:8
	ds_read2_b32 v[50:51], v31 offset0:33 offset1:41
	ds_read2_b32 v[52:53], v31 offset0:66 offset1:74
	ds_read2_b32 v[54:55], v31 offset0:99 offset1:107
	ds_read2_b32 v[56:57], v31 offset0:132 offset1:140
	ds_read2_b32 v[58:59], v31 offset0:165 offset1:173
	ds_read2_b32 v[60:61], v31 offset0:198 offset1:206
	ds_read2_b32 v[62:63], v31 offset0:231 offset1:239
	ds_read2_b32 v[64:65], v31 offset0:16 offset1:24
	ds_read2_b32 v[66:67], v31 offset0:49 offset1:57
	ds_read2_b32 v[68:69], v31 offset0:82 offset1:90
	ds_read2_b32 v[70:71], v31 offset0:115 offset1:123
	ds_read2_b32 v[72:73], v31 offset0:148 offset1:156
	ds_read2_b32 v[74:75], v31 offset0:181 offset1:189
	ds_read2_b32 v[76:77], v31 offset0:214 offset1:222
	ds_read2_b32 v[78:79], v31 offset0:247 offset1:255
	s_waitcnt lgkmcnt(8)
	v_cvt_pk_bf16_f32 v80, v48, v50
	v_cvt_pk_bf16_f32 v81, v52, v54
	v_cvt_pk_bf16_f32 v82, v56, v58
	v_cvt_pk_bf16_f32 v83, v60, v62
	v_cvt_pk_bf16_f32 v84, v49, v51
	v_cvt_pk_bf16_f32 v85, v53, v55
	v_cvt_pk_bf16_f32 v86, v57, v59
	v_cvt_pk_bf16_f32 v87, v61, v63
	s_waitcnt lgkmcnt(0)
	v_cvt_pk_bf16_f32 v88, v64, v66
	v_cvt_pk_bf16_f32 v89, v68, v70
	v_cvt_pk_bf16_f32 v90, v72, v74
	v_cvt_pk_bf16_f32 v91, v76, v78
	v_cvt_pk_bf16_f32 v92, v65, v67
	v_cvt_pk_bf16_f32 v93, v69, v71
	v_cvt_pk_bf16_f32 v94, v73, v75
	v_cvt_pk_bf16_f32 v95, v77, v79
	global_store_dwordx4 v120, v[80:83], s[88:89] offset:3072
	global_store_dwordx4 v121, v[84:87], s[88:89] offset:3072
	global_store_dwordx4 v122, v[88:91], s[88:89] offset:3072
	global_store_dwordx4 v123, v[92:95], s[88:89] offset:3072
	s_add_u32 s50, s50, 0x200000
	s_addc_u32 s51, s51, 0
	global_load_dwordx4 v[128:131], v100, s[50:51] nt
	global_load_dwordx4 v[132:135], v101, s[50:51] nt
	global_load_dwordx4 v[136:139], v102, s[50:51] nt
	global_load_dwordx4 v[140:143], v103, s[50:51] nt
	global_load_dwordx4 v[144:147], v104, s[50:51] nt
	global_load_dwordx4 v[148:151], v105, s[50:51] nt
	global_load_dwordx4 v[152:155], v106, s[50:51] nt
	global_load_dwordx4 v[156:159], v107, s[50:51] nt
	s_waitcnt vmcnt(16)
	ds_write2_b32 v32, v160, v161 offset1:1
	ds_write2_b32 v32, v162, v163 offset0:2 offset1:3
	ds_write2_b32 v33, v164, v165 offset1:1
	ds_write2_b32 v34, v166, v167 offset1:1
	ds_write2_b32 v35, v168, v169 offset1:1
	ds_write2_b32 v36, v170, v171 offset1:1
	ds_write2_b32 v37, v172, v173 offset1:1
	ds_write2_b32 v38, v174, v175 offset1:1
	ds_write2_b32 v39, v176, v177 offset1:1
	ds_write2_b32 v40, v178, v179 offset1:1
	ds_write2_b32 v41, v180, v181 offset1:1
	ds_write2_b32 v42, v182, v183 offset1:1
	ds_write2_b32 v43, v184, v185 offset1:1
	ds_write2_b32 v44, v186, v187 offset1:1
	ds_write2_b32 v45, v188, v189 offset1:1
	ds_write2_b32 v46, v190, v191 offset1:1
	s_waitcnt lgkmcnt(0)
	ds_read2_b32 v[48:49], v31 offset0:0 offset1:8
	ds_read2_b32 v[50:51], v31 offset0:33 offset1:41
	ds_read2_b32 v[52:53], v31 offset0:66 offset1:74
	ds_read2_b32 v[54:55], v31 offset0:99 offset1:107
	ds_read2_b32 v[56:57], v31 offset0:132 offset1:140
	ds_read2_b32 v[58:59], v31 offset0:165 offset1:173
	ds_read2_b32 v[60:61], v31 offset0:198 offset1:206
	ds_read2_b32 v[62:63], v31 offset0:231 offset1:239
	ds_read2_b32 v[64:65], v31 offset0:16 offset1:24
	ds_read2_b32 v[66:67], v31 offset0:49 offset1:57
	ds_read2_b32 v[68:69], v31 offset0:82 offset1:90
	ds_read2_b32 v[70:71], v31 offset0:115 offset1:123
	ds_read2_b32 v[72:73], v31 offset0:148 offset1:156
	ds_read2_b32 v[74:75], v31 offset0:181 offset1:189
	ds_read2_b32 v[76:77], v31 offset0:214 offset1:222
	ds_read2_b32 v[78:79], v31 offset0:247 offset1:255
	s_waitcnt lgkmcnt(8)
	v_cvt_pk_bf16_f32 v80, v48, v50
	v_cvt_pk_bf16_f32 v81, v52, v54
	v_cvt_pk_bf16_f32 v82, v56, v58
	v_cvt_pk_bf16_f32 v83, v60, v62
	v_cvt_pk_bf16_f32 v84, v49, v51
	v_cvt_pk_bf16_f32 v85, v53, v55
	v_cvt_pk_bf16_f32 v86, v57, v59
	v_cvt_pk_bf16_f32 v87, v61, v63
	s_waitcnt lgkmcnt(0)
; #define GAS __attribute__((address_space(1)))
; #define LAS __attribute__((address_space(3)))
; #define LDS_WAIT() asm volatile("s_waitcnt lgkmcnt(0)" ::: "memory")
; __device__ __forceinline__ void p0_transpose_item(const float* W, int ldw, int src_col0, int k0, bf16_t* WT, int ldk, int dst_row0, int dst_k0, LAS float* scr, int lane) {
; #pragma unroll
;     for (int i = 0; i < 8; ++i) { const int kk = 8 * i + (lane >> 3), n4 = 4 * (lane & 7);
;         const f32x4 w = *(const GAS f32x4*)(W + (size_t)(k0 + kk) * ldw + src_col0 + n4); LAS float* d = scr + kk * 33 + n4; d[0] = w[0]; d[1] = w[1]; d[2] = w[2]; d[3] = w[3]; }
;     LDS_WAIT(); asm volatile("" ::: "memory");
;     const int c = lane & 7;
; #pragma unroll
;     for (int j = 0; j < 4; ++j) { const int n = (lane >> 3) + 8 * j; const LAS float* s = scr + (8 * c) * 33 + n;
;         v4u o; o.x = pk2(s[0 * 33], s[1 * 33]); o.y = pk2(s[2 * 33], s[3 * 33]); o.z = pk2(s[4 * 33], s[5 * 33]); o.w = pk2(s[6 * 33], s[7 * 33]);
;         *(GAS v4u*)(WT + (size_t)(dst_row0 + n) * ldk + dst_k0 + k0 + 8 * c) = o; }
;     LDS_WAIT(); asm volatile("" ::: "memory");
; __global__ void __launch_bounds__(NWAVES * 64, 2) fwd(Args args) {
;     ...
;                 if (blockIdx.x < 64) for (int it = ((int)blockIdx.x - 32) * NWAVES + wave; it < I_BA + I_BB + I_O + I_UP + I_DN; it += 32 * NWAVES) {
;                     int r = it;
;                     if (r < I_BA) { const int kb = r / 32, nb = r % 32; p0_transpose_item(wba, 1024, 32 * nb, 64 * kb, WBAB_T, 1024, 32 * nb, 0, scr, lane); continue; } r -= I_BA;
;                     if (r < I_BB) { const int kb = r / 32, nb = r % 32; p0_transpose_item(wbb, 1024, 32 * nb, 64 * kb, WBAB_T, 1024, 32 * nb, 512, scr, lane); continue; } r -= I_BB;
;                     if (r < I_O) { const int kb = r / 32, nb = r % 32; p0_transpose_item(wo, 1024, 32 * nb, 64 * kb, WO_T, 1024, 32 * nb, 0, scr, lane); continue; } r -= I_O;
;                     if (r < I_UP) { const int kb = r / 128, nb = r % 128; p0_transpose_item(wup, FF, 32 * nb, 64 * kb, WUP_T, 1024, 32 * nb, 0, scr, lane); continue; } r -= I_UP;
;                     { const int kb = r / 32, nb = r % 32; p0_transpose_item(wdn, 1024, 32 * nb, 64 * kb, WDN_T, FF, 32 * nb, 0, scr, lane); }
	v_cvt_pk_bf16_f32 v88, v64, v66
	v_cvt_pk_bf16_f32 v89, v68, v70
	v_cvt_pk_bf16_f32 v90, v72, v74
	v_cvt_pk_bf16_f32 v91, v76, v78
	v_cvt_pk_bf16_f32 v92, v65, v67
	v_cvt_pk_bf16_f32 v93, v69, v71
	v_cvt_pk_bf16_f32 v94, v73, v75
	v_cvt_pk_bf16_f32 v95, v77, v79
	global_store_dwordx4 v120, v[80:83], s[76:77]
	global_store_dwordx4 v121, v[84:87], s[76:77]
	global_store_dwordx4 v122, v[88:91], s[76:77]
	global_store_dwordx4 v123, v[92:95], s[76:77]
	s_add_u32 s50, s50, 0x200000
	s_addc_u32 s51, s51, 0
	global_load_dwordx4 v[160:163], v100, s[50:51] nt
	global_load_dwordx4 v[164:167], v101, s[50:51] nt
	global_load_dwordx4 v[168:171], v102, s[50:51] nt
	global_load_dwordx4 v[172:175], v103, s[50:51] nt
	global_load_dwordx4 v[176:179], v104, s[50:51] nt
	global_load_dwordx4 v[180:183], v105, s[50:51] nt
	global_load_dwordx4 v[184:187], v106, s[50:51] nt
	global_load_dwordx4 v[188:191], v107, s[50:51] nt
	s_waitcnt vmcnt(16)
	ds_write2_b32 v32, v192, v193 offset1:1
	ds_write2_b32 v32, v194, v195 offset0:2 offset1:3
	ds_write2_b32 v33, v196, v197 offset1:1
	ds_write2_b32 v34, v198, v199 offset1:1
	ds_write2_b32 v35, v200, v201 offset1:1
	ds_write2_b32 v36, v202, v203 offset1:1
	ds_write2_b32 v37, v204, v205 offset1:1
	ds_write2_b32 v38, v206, v207 offset1:1
	ds_write2_b32 v39, v208, v209 offset1:1
	ds_write2_b32 v40, v210, v211 offset1:1
	ds_write2_b32 v41, v212, v213 offset1:1
	ds_write2_b32 v42, v214, v215 offset1:1
	ds_write2_b32 v43, v216, v217 offset1:1
	ds_write2_b32 v44, v218, v219 offset1:1
	ds_write2_b32 v45, v220, v221 offset1:1
	ds_write2_b32 v46, v222, v223 offset1:1
	s_waitcnt lgkmcnt(0)
	ds_read2_b32 v[48:49], v31 offset0:0 offset1:8
	ds_read2_b32 v[50:51], v31 offset0:33 offset1:41
	ds_read2_b32 v[52:53], v31 offset0:66 offset1:74
	ds_read2_b32 v[54:55], v31 offset0:99 offset1:107
	ds_read2_b32 v[56:57], v31 offset0:132 offset1:140
	ds_read2_b32 v[58:59], v31 offset0:165 offset1:173
	ds_read2_b32 v[60:61], v31 offset0:198 offset1:206
	ds_read2_b32 v[62:63], v31 offset0:231 offset1:239
	ds_read2_b32 v[64:65], v31 offset0:16 offset1:24
	ds_read2_b32 v[66:67], v31 offset0:49 offset1:57
	ds_read2_b32 v[68:69], v31 offset0:82 offset1:90
	ds_read2_b32 v[70:71], v31 offset0:115 offset1:123
	ds_read2_b32 v[72:73], v31 offset0:148 offset1:156
	ds_read2_b32 v[74:75], v31 offset0:181 offset1:189
	ds_read2_b32 v[76:77], v31 offset0:214 offset1:222
	ds_read2_b32 v[78:79], v31 offset0:247 offset1:255
	s_waitcnt lgkmcnt(8)
	v_cvt_pk_bf16_f32 v80, v48, v50
	v_cvt_pk_bf16_f32 v81, v52, v54
	v_cvt_pk_bf16_f32 v82, v56, v58
	v_cvt_pk_bf16_f32 v83, v60, v62
	v_cvt_pk_bf16_f32 v84, v49, v51
	v_cvt_pk_bf16_f32 v85, v53, v55
	v_cvt_pk_bf16_f32 v86, v57, v59
	v_cvt_pk_bf16_f32 v87, v61, v63
	s_waitcnt lgkmcnt(0)
	v_cvt_pk_bf16_f32 v88, v64, v66
	v_cvt_pk_bf16_f32 v89, v68, v70
	v_cvt_pk_bf16_f32 v90, v72, v74
	v_cvt_pk_bf16_f32 v91, v76, v78
	v_cvt_pk_bf16_f32 v92, v65, v67
	v_cvt_pk_bf16_f32 v93, v69, v71
	v_cvt_pk_bf16_f32 v94, v73, v75
	v_cvt_pk_bf16_f32 v95, v77, v79
	global_store_dwordx4 v120, v[80:83], s[76:77] offset:1024
	global_store_dwordx4 v121, v[84:87], s[76:77] offset:1024
	global_store_dwordx4 v122, v[88:91], s[76:77] offset:1024
	global_store_dwordx4 v123, v[92:95], s[76:77] offset:1024
	s_waitcnt vmcnt(8)
	ds_write2_b32 v32, v128, v129 offset1:1
	ds_write2_b32 v32, v130, v131 offset0:2 offset1:3
	ds_write2_b32 v33, v132, v133 offset1:1
	ds_write2_b32 v34, v134, v135 offset1:1
	ds_write2_b32 v35, v136, v137 offset1:1
	ds_write2_b32 v36, v138, v139 offset1:1
	ds_write2_b32 v37, v140, v141 offset1:1
	ds_write2_b32 v38, v142, v143 offset1:1
	ds_write2_b32 v39, v144, v145 offset1:1
	ds_write2_b32 v40, v146, v147 offset1:1
	ds_write2_b32 v41, v148, v149 offset1:1
	ds_write2_b32 v42, v150, v151 offset1:1
	ds_write2_b32 v43, v152, v153 offset1:1
	ds_write2_b32 v44, v154, v155 offset1:1
	ds_write2_b32 v45, v156, v157 offset1:1
	ds_write2_b32 v46, v158, v159 offset1:1
	s_waitcnt lgkmcnt(0)
; #define GAS __attribute__((address_space(1)))
; #define LAS __attribute__((address_space(3)))
; #define LDS_WAIT() asm volatile("s_waitcnt lgkmcnt(0)" ::: "memory")
; __device__ __forceinline__ void p0_transpose_item(const float* W, int ldw, int src_col0, int k0, bf16_t* WT, int ldk, int dst_row0, int dst_k0, LAS float* scr, int lane) {
; #pragma unroll
;     for (int i = 0; i < 8; ++i) { const int kk = 8 * i + (lane >> 3), n4 = 4 * (lane & 7);
;         const f32x4 w = *(const GAS f32x4*)(W + (size_t)(k0 + kk) * ldw + src_col0 + n4); LAS float* d = scr + kk * 33 + n4; d[0] = w[0]; d[1] = w[1]; d[2] = w[2]; d[3] = w[3]; }
;     LDS_WAIT(); asm volatile("" ::: "memory");
;     const int c = lane & 7;
; #pragma unroll
;     for (int j = 0; j < 4; ++j) { const int n = (lane >> 3) + 8 * j; const LAS float* s = scr + (8 * c) * 33 + n;
;         v4u o; o.x = pk2(s[0 * 33], s[1 * 33]); o.y = pk2(s[2 * 33], s[3 * 33]); o.z = pk2(s[4 * 33], s[5 * 33]); o.w = pk2(s[6 * 33], s[7 * 33]);
;         *(GAS v4u*)(WT + (size_t)(dst_row0 + n) * ldk + dst_k0 + k0 + 8 * c) = o; }
;     LDS_WAIT(); asm volatile("" ::: "memory");
; __global__ void __launch_bounds__(NWAVES * 64, 2) fwd(Args args) {
;     ...
;                 if (blockIdx.x < 64) for (int it = ((int)blockIdx.x - 32) * NWAVES + wave; it < I_BA + I_BB + I_O + I_UP + I_DN; it += 32 * NWAVES) {
;                     int r = it;
;                     if (r < I_BA) { const int kb = r / 32, nb = r % 32; p0_transpose_item(wba, 1024, 32 * nb, 64 * kb, WBAB_T, 1024, 32 * nb, 0, scr, lane); continue; } r -= I_BA;
;                     if (r < I_BB) { const int kb = r / 32, nb = r % 32; p0_transpose_item(wbb, 1024, 32 * nb, 64 * kb, WBAB_T, 1024, 32 * nb, 512, scr, lane); continue; } r -= I_BB;
;                     if (r < I_O) { const int kb = r / 32, nb = r % 32; p0_transpose_item(wo, 1024, 32 * nb, 64 * kb, WO_T, 1024, 32 * nb, 0, scr, lane); continue; } r -= I_O;
;                     if (r < I_UP) { const int kb = r / 128, nb = r % 128; p0_transpose_item(wup, FF, 32 * nb, 64 * kb, WUP_T, 1024, 32 * nb, 0, scr, lane); continue; } r -= I_UP;
;                     { const int kb = r / 32, nb = r % 32; p0_transpose_item(wdn, 1024, 32 * nb, 64 * kb, WDN_T, FF, 32 * nb, 0, scr, lane); }
	ds_read2_b32 v[48:49], v31 offset0:0 offset1:8
	ds_read2_b32 v[50:51], v31 offset0:33 offset1:41
	ds_read2_b32 v[52:53], v31 offset0:66 offset1:74
	ds_read2_b32 v[54:55], v31 offset0:99 offset1:107
	ds_read2_b32 v[56:57], v31 offset0:132 offset1:140
	ds_read2_b32 v[58:59], v31 offset0:165 offset1:173
	ds_read2_b32 v[60:61], v31 offset0:198 offset1:206
	ds_read2_b32 v[62:63], v31 offset0:231 offset1:239
	ds_read2_b32 v[64:65], v31 offset0:16 offset1:24
	ds_read2_b32 v[66:67], v31 offset0:49 offset1:57
	ds_read2_b32 v[68:69], v31 offset0:82 offset1:90
	ds_read2_b32 v[70:71], v31 offset0:115 offset1:123
	ds_read2_b32 v[72:73], v31 offset0:148 offset1:156
	ds_read2_b32 v[74:75], v31 offset0:181 offset1:189
	ds_read2_b32 v[76:77], v31 offset0:214 offset1:222
	ds_read2_b32 v[78:79], v31 offset0:247 offset1:255
	s_waitcnt lgkmcnt(8)
	v_cvt_pk_bf16_f32 v80, v48, v50
	v_cvt_pk_bf16_f32 v81, v52, v54
	v_cvt_pk_bf16_f32 v82, v56, v58
	v_cvt_pk_bf16_f32 v83, v60, v62
	v_cvt_pk_bf16_f32 v84, v49, v51
	v_cvt_pk_bf16_f32 v85, v53, v55
	v_cvt_pk_bf16_f32 v86, v57, v59
	v_cvt_pk_bf16_f32 v87, v61, v63
	s_waitcnt lgkmcnt(0)
	v_cvt_pk_bf16_f32 v88, v64, v66
	v_cvt_pk_bf16_f32 v89, v68, v70
	v_cvt_pk_bf16_f32 v90, v72, v74
	v_cvt_pk_bf16_f32 v91, v76, v78
	v_cvt_pk_bf16_f32 v92, v65, v67
	v_cvt_pk_bf16_f32 v93, v69, v71
	v_cvt_pk_bf16_f32 v94, v73, v75
	v_cvt_pk_bf16_f32 v95, v77, v79
	global_store_dwordx4 v120, v[80:83], s[76:77] offset:2048
	global_store_dwordx4 v121, v[84:87], s[76:77] offset:2048
	global_store_dwordx4 v122, v[88:91], s[76:77] offset:2048
	global_store_dwordx4 v123, v[92:95], s[76:77] offset:2048
	s_waitcnt vmcnt(0)
	ds_write2_b32 v32, v160, v161 offset1:1
	ds_write2_b32 v32, v162, v163 offset0:2 offset1:3
	ds_write2_b32 v33, v164, v165 offset1:1
	ds_write2_b32 v34, v166, v167 offset1:1
	ds_write2_b32 v35, v168, v169 offset1:1
	ds_write2_b32 v36, v170, v171 offset1:1
	ds_write2_b32 v37, v172, v173 offset1:1
	ds_write2_b32 v38, v174, v175 offset1:1
	ds_write2_b32 v39, v176, v177 offset1:1
	ds_write2_b32 v40, v178, v179 offset1:1
	ds_write2_b32 v41, v180, v181 offset1:1
	ds_write2_b32 v42, v182, v183 offset1:1
	ds_write2_b32 v43, v184, v185 offset1:1
	ds_write2_b32 v44, v186, v187 offset1:1
	ds_write2_b32 v45, v188, v189 offset1:1
	ds_write2_b32 v46, v190, v191 offset1:1
	s_waitcnt lgkmcnt(0)
	ds_read2_b32 v[48:49], v31 offset0:0 offset1:8
	ds_read2_b32 v[50:51], v31 offset0:33 offset1:41
	ds_read2_b32 v[52:53], v31 offset0:66 offset1:74
	ds_read2_b32 v[54:55], v31 offset0:99 offset1:107
	ds_read2_b32 v[56:57], v31 offset0:132 offset1:140
	ds_read2_b32 v[58:59], v31 offset0:165 offset1:173
	ds_read2_b32 v[60:61], v31 offset0:198 offset1:206
	ds_read2_b32 v[62:63], v31 offset0:231 offset1:239
	ds_read2_b32 v[64:65], v31 offset0:16 offset1:24
	ds_read2_b32 v[66:67], v31 offset0:49 offset1:57
	ds_read2_b32 v[68:69], v31 offset0:82 offset1:90
	ds_read2_b32 v[70:71], v31 offset0:115 offset1:123
	ds_read2_b32 v[72:73], v31 offset0:148 offset1:156
	ds_read2_b32 v[74:75], v31 offset0:181 offset1:189
	ds_read2_b32 v[76:77], v31 offset0:214 offset1:222
	ds_read2_b32 v[78:79], v31 offset0:247 offset1:255
	s_waitcnt lgkmcnt(8)
	v_cvt_pk_bf16_f32 v80, v48, v50
	v_cvt_pk_bf16_f32 v81, v52, v54
	v_cvt_pk_bf16_f32 v82, v56, v58
	v_cvt_pk_bf16_f32 v83, v60, v62
	v_cvt_pk_bf16_f32 v84, v49, v51
	v_cvt_pk_bf16_f32 v85, v53, v55
	v_cvt_pk_bf16_f32 v86, v57, v59
	v_cvt_pk_bf16_f32 v87, v61, v63
	s_waitcnt lgkmcnt(0)
	v_cvt_pk_bf16_f32 v88, v64, v66
	v_cvt_pk_bf16_f32 v89, v68, v70
	v_cvt_pk_bf16_f32 v90, v72, v74
	v_cvt_pk_bf16_f32 v91, v76, v78
	v_cvt_pk_bf16_f32 v92, v65, v67
	v_cvt_pk_bf16_f32 v93, v69, v71
	v_cvt_pk_bf16_f32 v94, v73, v75
	v_cvt_pk_bf16_f32 v95, v77, v79
	global_store_dwordx4 v120, v[80:83], s[76:77] offset:3072
	global_store_dwordx4 v121, v[84:87], s[76:77] offset:3072
	global_store_dwordx4 v122, v[88:91], s[76:77] offset:3072
	global_store_dwordx4 v123, v[92:95], s[76:77] offset:3072
